# v26 plus projection epilogue output stores as full 128-byte lines: 4x4 DPP quad transpose of the 16-byte pieces so 8 lanes cover one row
# speedup vs baseline: 1.0492x; 1.0098x over previous
.Lpe_entry_L0:
	s_nop 7
	s_and_b32 s24, s99, 7
	s_lshl_b32 s24, s24, 3
	s_bfe_u32 s25, s99, 0x30003
	s_or_b32 s24, s24, s25
	s_lshr_b32 s25, s99, 6
	v_readfirstlane_b32 s26, v178
	v_readlane_b32 s72, v254, 0
	v_readlane_b32 s73, v254, 1
	s_lshr_b32 s26, s26, 6
	s_lshr_b32 s27, s26, 2
	s_and_b32 s28, s26, 3
	s_lshl_b32 s29, s24, 8
	s_lshl_b32 s30, s27, 7
	s_add_u32 s29, s29, s30
	s_lshl_b32 s30, s25, 8
	s_lshl_b32 s31, s28, 6
	s_add_u32 s30, s30, s31
	s_lshl_b32 s31, s29, 5
	s_add_u32 s94, s72, 0x1ad20000
	s_addc_u32 s95, s73, 0
	s_add_u32 s94, s94, s31
	s_addc_u32 s95, s95, 0
	v_and_b32_e32 v197, 31, v179
	v_lshrrev_b32_e32 v146, 5, v179
	v_lshlrev_b32_e32 v180, 5, v197
	v_lshlrev_b32_e32 v146, 4, v146
	global_load_dwordx4 v[128:131], v180, s[94:95] offset:0
	global_load_dwordx4 v[132:135], v180, s[94:95] offset:16
	global_load_dwordx4 v[136:139], v180, s[94:95] offset:1024
	global_load_dwordx4 v[140:143], v180, s[94:95] offset:1040
	global_load_dwordx4 v[164:167], v180, s[94:95] offset:2048
	global_load_dwordx4 v[168:171], v180, s[94:95] offset:2064
	global_load_dwordx4 v[246:249], v180, s[94:95] offset:3072
	global_load_dwordx4 v[250:253], v180, s[94:95] offset:3088
	s_mul_i32 s31, s29, 0x2200
	s_lshl_b32 s32, s30, 1
	s_add_u32 s31, s31, s32
	s_add_u32 s74, s72, 0xc120000
	s_addc_u32 s75, s73, 0
	s_add_u32 s74, s74, s31
	s_addc_u32 s75, s75, 0
	v_and_b32_e32 v181, 0x1c, v197
	v_mul_u32_u24_e32 v181, 0x2200, v181
	v_and_b32_e32 v198, 3, v197
	v_lshl_add_u32 v181, v198, 5, v181
	v_add_u32_e32 v181, v181, v146
	s_sub_u32 s34, s25, 4
	s_cmp_lt_u32 s34, 2
	s_cbranch_scc1 .Lpe_vt_all_L0
	s_cmp_eq_u32 s25, 8
	s_cbranch_scc0 .Lpe_notv_L0
	s_barrier
	s_cmp_ge_u32 s28, 2
	s_cbranch_scc1 .Lpe_vt_L0
	s_branch .Lpe_notv_L0

.Lpe_norope_0_L0:
	v_cvt_pk_bf16_f32 v0, v0, v1
	v_cvt_pk_bf16_f32 v1, v2, v3
	v_cvt_pk_bf16_f32 v2, v4, v5
	v_cvt_pk_bf16_f32 v3, v6, v7
	v_cvt_pk_bf16_f32 v4, v8, v9
	v_cvt_pk_bf16_f32 v5, v10, v11
	v_cvt_pk_bf16_f32 v6, v12, v13
	v_cvt_pk_bf16_f32 v7, v14, v15
	v_cvt_pk_bf16_f32 v16, v16, v17
	v_cvt_pk_bf16_f32 v17, v18, v19
	v_cvt_pk_bf16_f32 v18, v20, v21
	v_cvt_pk_bf16_f32 v19, v22, v23
	v_cvt_pk_bf16_f32 v20, v24, v25
	v_cvt_pk_bf16_f32 v21, v26, v27
	v_cvt_pk_bf16_f32 v22, v28, v29
	v_cvt_pk_bf16_f32 v23, v30, v31
	v_permlane32_swap_b32_e32 v0, v2
	v_permlane32_swap_b32_e32 v1, v3
	v_permlane32_swap_b32_e32 v4, v6
	v_permlane32_swap_b32_e32 v5, v7
	v_permlane32_swap_b32_e32 v16, v18
	v_permlane32_swap_b32_e32 v17, v19
	v_permlane32_swap_b32_e32 v20, v22
	v_permlane32_swap_b32_e32 v21, v23
	s_nop 1
	s_mov_b32 vcc_lo, 0x55555555
	s_mov_b32 vcc_hi, 0x55555555
	v_cndmask_b32_dpp v128, v4, v0, vcc quad_perm:[1,0,3,2] row_mask:0xf bank_mask:0xf
	v_cndmask_b32_dpp v129, v5, v1, vcc quad_perm:[1,0,3,2] row_mask:0xf bank_mask:0xf
	v_cndmask_b32_dpp v130, v6, v2, vcc quad_perm:[1,0,3,2] row_mask:0xf bank_mask:0xf
	v_cndmask_b32_dpp v131, v7, v3, vcc quad_perm:[1,0,3,2] row_mask:0xf bank_mask:0xf
	v_cndmask_b32_dpp v136, v20, v16, vcc quad_perm:[1,0,3,2] row_mask:0xf bank_mask:0xf
	v_cndmask_b32_dpp v137, v21, v17, vcc quad_perm:[1,0,3,2] row_mask:0xf bank_mask:0xf
	v_cndmask_b32_dpp v138, v22, v18, vcc quad_perm:[1,0,3,2] row_mask:0xf bank_mask:0xf
	v_cndmask_b32_dpp v139, v23, v19, vcc quad_perm:[1,0,3,2] row_mask:0xf bank_mask:0xf
	s_mov_b32 vcc_lo, 0xaaaaaaaa
	s_mov_b32 vcc_hi, 0xaaaaaaaa
	v_cndmask_b32_dpp v132, v0, v4, vcc quad_perm:[1,0,3,2] row_mask:0xf bank_mask:0xf
	v_cndmask_b32_dpp v133, v1, v5, vcc quad_perm:[1,0,3,2] row_mask:0xf bank_mask:0xf
	v_cndmask_b32_dpp v134, v2, v6, vcc quad_perm:[1,0,3,2] row_mask:0xf bank_mask:0xf
	v_cndmask_b32_dpp v135, v3, v7, vcc quad_perm:[1,0,3,2] row_mask:0xf bank_mask:0xf
	v_cndmask_b32_dpp v140, v16, v20, vcc quad_perm:[1,0,3,2] row_mask:0xf bank_mask:0xf
	v_cndmask_b32_dpp v141, v17, v21, vcc quad_perm:[1,0,3,2] row_mask:0xf bank_mask:0xf
	v_cndmask_b32_dpp v142, v18, v22, vcc quad_perm:[1,0,3,2] row_mask:0xf bank_mask:0xf
	v_cndmask_b32_dpp v143, v19, v23, vcc quad_perm:[1,0,3,2] row_mask:0xf bank_mask:0xf
	s_nop 1
	s_mov_b32 vcc_lo, 0x33333333
	s_mov_b32 vcc_hi, 0x33333333
	v_cndmask_b32_dpp v0, v136, v128, vcc quad_perm:[2,3,0,1] row_mask:0xf bank_mask:0xf
	v_cndmask_b32_dpp v1, v137, v129, vcc quad_perm:[2,3,0,1] row_mask:0xf bank_mask:0xf
	v_cndmask_b32_dpp v2, v138, v130, vcc quad_perm:[2,3,0,1] row_mask:0xf bank_mask:0xf
	v_cndmask_b32_dpp v3, v139, v131, vcc quad_perm:[2,3,0,1] row_mask:0xf bank_mask:0xf
	v_cndmask_b32_dpp v4, v140, v132, vcc quad_perm:[2,3,0,1] row_mask:0xf bank_mask:0xf
	v_cndmask_b32_dpp v5, v141, v133, vcc quad_perm:[2,3,0,1] row_mask:0xf bank_mask:0xf
	v_cndmask_b32_dpp v6, v142, v134, vcc quad_perm:[2,3,0,1] row_mask:0xf bank_mask:0xf
	v_cndmask_b32_dpp v7, v143, v135, vcc quad_perm:[2,3,0,1] row_mask:0xf bank_mask:0xf
	s_mov_b32 vcc_lo, 0xcccccccc
	s_mov_b32 vcc_hi, 0xcccccccc
	v_cndmask_b32_dpp v16, v128, v136, vcc quad_perm:[2,3,0,1] row_mask:0xf bank_mask:0xf
	v_cndmask_b32_dpp v17, v129, v137, vcc quad_perm:[2,3,0,1] row_mask:0xf bank_mask:0xf
	v_cndmask_b32_dpp v18, v130, v138, vcc quad_perm:[2,3,0,1] row_mask:0xf bank_mask:0xf
	v_cndmask_b32_dpp v19, v131, v139, vcc quad_perm:[2,3,0,1] row_mask:0xf bank_mask:0xf
	v_cndmask_b32_dpp v20, v132, v140, vcc quad_perm:[2,3,0,1] row_mask:0xf bank_mask:0xf
	v_cndmask_b32_dpp v21, v133, v141, vcc quad_perm:[2,3,0,1] row_mask:0xf bank_mask:0xf
	v_cndmask_b32_dpp v22, v134, v142, vcc quad_perm:[2,3,0,1] row_mask:0xf bank_mask:0xf
	v_cndmask_b32_dpp v23, v135, v143, vcc quad_perm:[2,3,0,1] row_mask:0xf bank_mask:0xf
	s_add_u32 s76, s74, 0x0
	s_addc_u32 s77, s75, 0
	global_store_dwordx4 v181, v[0:3], s[76:77]
	s_add_u32 s76, s74, 0x2200
	s_addc_u32 s77, s75, 0
	global_store_dwordx4 v181, v[4:7], s[76:77]
	s_add_u32 s76, s74, 0x4400
	s_addc_u32 s77, s75, 0
	global_store_dwordx4 v181, v[16:19], s[76:77]
	s_add_u32 s76, s74, 0x6600
	s_addc_u32 s77, s75, 0
	global_store_dwordx4 v181, v[20:23], s[76:77]
	s_add_u32 s74, s74, 0x44000
	s_addc_u32 s75, s75, 0
	v_pk_mul_f32 v[32:33], v[32:33], v[172:173] op_sel:[0,1] op_sel_hi:[1,1]
	v_pk_mul_f32 v[34:35], v[34:35], v[172:173] op_sel:[0,1] op_sel_hi:[1,1]
	v_pk_mul_f32 v[36:37], v[36:37], v[172:173] op_sel:[0,1] op_sel_hi:[1,1]
	v_pk_mul_f32 v[38:39], v[38:39], v[172:173] op_sel:[0,1] op_sel_hi:[1,1]
	v_pk_mul_f32 v[40:41], v[40:41], v[172:173] op_sel:[0,1] op_sel_hi:[1,1]
	v_pk_mul_f32 v[42:43], v[42:43], v[172:173] op_sel:[0,1] op_sel_hi:[1,1]
	v_pk_mul_f32 v[44:45], v[44:45], v[172:173] op_sel:[0,1] op_sel_hi:[1,1]
	v_pk_mul_f32 v[46:47], v[46:47], v[172:173] op_sel:[0,1] op_sel_hi:[1,1]
	v_pk_mul_f32 v[48:49], v[48:49], v[172:173] op_sel:[0,1] op_sel_hi:[1,1]
	v_pk_mul_f32 v[50:51], v[50:51], v[172:173] op_sel:[0,1] op_sel_hi:[1,1]
	v_pk_mul_f32 v[52:53], v[52:53], v[172:173] op_sel:[0,1] op_sel_hi:[1,1]
	v_pk_mul_f32 v[54:55], v[54:55], v[172:173] op_sel:[0,1] op_sel_hi:[1,1]
	v_pk_mul_f32 v[56:57], v[56:57], v[172:173] op_sel:[0,1] op_sel_hi:[1,1]
	v_pk_mul_f32 v[58:59], v[58:59], v[172:173] op_sel:[0,1] op_sel_hi:[1,1]
	v_pk_mul_f32 v[60:61], v[60:61], v[172:173] op_sel:[0,1] op_sel_hi:[1,1]
	v_pk_mul_f32 v[62:63], v[62:63], v[172:173] op_sel:[0,1] op_sel_hi:[1,1]
	v_pk_mul_f32 v[32:33], v[32:33], v[198:199]
	v_pk_mul_f32 v[34:35], v[34:35], v[200:201]
	v_pk_mul_f32 v[36:37], v[36:37], v[202:203]
	v_pk_mul_f32 v[38:39], v[38:39], v[204:205]
	v_pk_mul_f32 v[40:41], v[40:41], v[206:207]
	v_pk_mul_f32 v[42:43], v[42:43], v[208:209]
	v_pk_mul_f32 v[44:45], v[44:45], v[210:211]
	v_pk_mul_f32 v[46:47], v[46:47], v[212:213]
	v_pk_mul_f32 v[48:49], v[48:49], v[214:215]
	v_pk_mul_f32 v[50:51], v[50:51], v[216:217]
	v_pk_mul_f32 v[52:53], v[52:53], v[218:219]
	v_pk_mul_f32 v[54:55], v[54:55], v[220:221]
	v_pk_mul_f32 v[56:57], v[56:57], v[222:223]
	v_pk_mul_f32 v[58:59], v[58:59], v[224:225]
	v_pk_mul_f32 v[60:61], v[60:61], v[226:227]
	v_pk_mul_f32 v[62:63], v[62:63], v[228:229]
	s_cmp_eq_u32 s37, 0
	s_cbranch_scc1 .Lpe_norope_1_L0
	s_waitcnt vmcnt(4)
	v_pk_mul_f32 v[128:129], v[48:49], v[148:149]
	v_pk_mul_f32 v[164:165], v[48:49], v[230:231]
	v_pk_mul_f32 v[130:131], v[50:51], v[150:151]
	v_pk_mul_f32 v[166:167], v[50:51], v[232:233]
	v_pk_mul_f32 v[132:133], v[52:53], v[152:153]
	v_pk_mul_f32 v[168:169], v[52:53], v[234:235]
	v_pk_mul_f32 v[134:135], v[54:55], v[154:155]
	v_pk_mul_f32 v[170:171], v[54:55], v[236:237]
	v_pk_mul_f32 v[136:137], v[56:57], v[156:157]
	v_pk_mul_f32 v[246:247], v[56:57], v[238:239]
	v_pk_mul_f32 v[138:139], v[58:59], v[158:159]
	v_pk_mul_f32 v[248:249], v[58:59], v[240:241]
	v_pk_mul_f32 v[140:141], v[60:61], v[160:161]
	v_pk_mul_f32 v[250:251], v[60:61], v[242:243]
	v_pk_mul_f32 v[142:143], v[62:63], v[162:163]
	v_pk_mul_f32 v[252:253], v[62:63], v[244:245]
	v_pk_fma_f32 v[48:49], v[32:33], v[148:149], v[164:165]
	v_pk_fma_f32 v[32:33], v[32:33], v[230:231], v[128:129] neg_lo:[0,0,1] neg_hi:[0,0,1]
	v_pk_fma_f32 v[50:51], v[34:35], v[150:151], v[166:167]
	v_pk_fma_f32 v[34:35], v[34:35], v[232:233], v[130:131] neg_lo:[0,0,1] neg_hi:[0,0,1]
	v_pk_fma_f32 v[52:53], v[36:37], v[152:153], v[168:169]
	v_pk_fma_f32 v[36:37], v[36:37], v[234:235], v[132:133] neg_lo:[0,0,1] neg_hi:[0,0,1]
	v_pk_fma_f32 v[54:55], v[38:39], v[154:155], v[170:171]
	v_pk_fma_f32 v[38:39], v[38:39], v[236:237], v[134:135] neg_lo:[0,0,1] neg_hi:[0,0,1]
	v_pk_fma_f32 v[56:57], v[40:41], v[156:157], v[246:247]
	v_pk_fma_f32 v[40:41], v[40:41], v[238:239], v[136:137] neg_lo:[0,0,1] neg_hi:[0,0,1]
	v_pk_fma_f32 v[58:59], v[42:43], v[158:159], v[248:249]
	v_pk_fma_f32 v[42:43], v[42:43], v[240:241], v[138:139] neg_lo:[0,0,1] neg_hi:[0,0,1]
	v_pk_fma_f32 v[60:61], v[44:45], v[160:161], v[250:251]
	v_pk_fma_f32 v[44:45], v[44:45], v[242:243], v[140:141] neg_lo:[0,0,1] neg_hi:[0,0,1]
	v_pk_fma_f32 v[62:63], v[46:47], v[162:163], v[252:253]
	v_pk_fma_f32 v[46:47], v[46:47], v[244:245], v[142:143] neg_lo:[0,0,1] neg_hi:[0,0,1]
	s_add_u32 s96, s96, 0x1000
	s_addc_u32 s97, s97, 0
	s_add_u32 s100, s100, 0x1000
	s_addc_u32 s101, s101, 0
	global_load_dwordx4 v[230:233], v180, s[96:97] offset:0
	global_load_dwordx4 v[234:237], v180, s[96:97] offset:32
	global_load_dwordx4 v[238:241], v180, s[96:97] offset:64
	global_load_dwordx4 v[242:245], v180, s[96:97] offset:96
	global_load_dwordx4 v[148:151], v180, s[100:101] offset:0
	global_load_dwordx4 v[152:155], v180, s[100:101] offset:32
	global_load_dwordx4 v[156:159], v180, s[100:101] offset:64
	global_load_dwordx4 v[160:163], v180, s[100:101] offset:96
.Lpe_norope_1_L0:
	v_cvt_pk_bf16_f32 v32, v32, v33
	v_cvt_pk_bf16_f32 v33, v34, v35
	v_cvt_pk_bf16_f32 v34, v36, v37
	v_cvt_pk_bf16_f32 v35, v38, v39
	v_cvt_pk_bf16_f32 v36, v40, v41
	v_cvt_pk_bf16_f32 v37, v42, v43
	v_cvt_pk_bf16_f32 v38, v44, v45
	v_cvt_pk_bf16_f32 v39, v46, v47
	v_cvt_pk_bf16_f32 v48, v48, v49
	v_cvt_pk_bf16_f32 v49, v50, v51
	v_cvt_pk_bf16_f32 v50, v52, v53
	v_cvt_pk_bf16_f32 v51, v54, v55
	v_cvt_pk_bf16_f32 v52, v56, v57
	v_cvt_pk_bf16_f32 v53, v58, v59
	v_cvt_pk_bf16_f32 v54, v60, v61
	v_cvt_pk_bf16_f32 v55, v62, v63
	v_permlane32_swap_b32_e32 v32, v34
	v_permlane32_swap_b32_e32 v33, v35
	v_permlane32_swap_b32_e32 v36, v38
	v_permlane32_swap_b32_e32 v37, v39
	v_permlane32_swap_b32_e32 v48, v50
	v_permlane32_swap_b32_e32 v49, v51
	v_permlane32_swap_b32_e32 v52, v54
	v_permlane32_swap_b32_e32 v53, v55
	s_nop 1
	s_mov_b32 vcc_lo, 0x55555555
	s_mov_b32 vcc_hi, 0x55555555
	v_cndmask_b32_dpp v128, v36, v32, vcc quad_perm:[1,0,3,2] row_mask:0xf bank_mask:0xf
	v_cndmask_b32_dpp v129, v37, v33, vcc quad_perm:[1,0,3,2] row_mask:0xf bank_mask:0xf
	v_cndmask_b32_dpp v130, v38, v34, vcc quad_perm:[1,0,3,2] row_mask:0xf bank_mask:0xf
	v_cndmask_b32_dpp v131, v39, v35, vcc quad_perm:[1,0,3,2] row_mask:0xf bank_mask:0xf
	v_cndmask_b32_dpp v136, v52, v48, vcc quad_perm:[1,0,3,2] row_mask:0xf bank_mask:0xf
	v_cndmask_b32_dpp v137, v53, v49, vcc quad_perm:[1,0,3,2] row_mask:0xf bank_mask:0xf
	v_cndmask_b32_dpp v138, v54, v50, vcc quad_perm:[1,0,3,2] row_mask:0xf bank_mask:0xf
	v_cndmask_b32_dpp v139, v55, v51, vcc quad_perm:[1,0,3,2] row_mask:0xf bank_mask:0xf
	s_mov_b32 vcc_lo, 0xaaaaaaaa
	s_mov_b32 vcc_hi, 0xaaaaaaaa
	v_cndmask_b32_dpp v132, v32, v36, vcc quad_perm:[1,0,3,2] row_mask:0xf bank_mask:0xf
	v_cndmask_b32_dpp v133, v33, v37, vcc quad_perm:[1,0,3,2] row_mask:0xf bank_mask:0xf
	v_cndmask_b32_dpp v134, v34, v38, vcc quad_perm:[1,0,3,2] row_mask:0xf bank_mask:0xf
	v_cndmask_b32_dpp v135, v35, v39, vcc quad_perm:[1,0,3,2] row_mask:0xf bank_mask:0xf
	v_cndmask_b32_dpp v140, v48, v52, vcc quad_perm:[1,0,3,2] row_mask:0xf bank_mask:0xf
	v_cndmask_b32_dpp v141, v49, v53, vcc quad_perm:[1,0,3,2] row_mask:0xf bank_mask:0xf
	v_cndmask_b32_dpp v142, v50, v54, vcc quad_perm:[1,0,3,2] row_mask:0xf bank_mask:0xf
	v_cndmask_b32_dpp v143, v51, v55, vcc quad_perm:[1,0,3,2] row_mask:0xf bank_mask:0xf
	s_nop 1
	s_mov_b32 vcc_lo, 0x33333333
	s_mov_b32 vcc_hi, 0x33333333
	v_cndmask_b32_dpp v32, v136, v128, vcc quad_perm:[2,3,0,1] row_mask:0xf bank_mask:0xf
	v_cndmask_b32_dpp v33, v137, v129, vcc quad_perm:[2,3,0,1] row_mask:0xf bank_mask:0xf
	v_cndmask_b32_dpp v34, v138, v130, vcc quad_perm:[2,3,0,1] row_mask:0xf bank_mask:0xf
	v_cndmask_b32_dpp v35, v139, v131, vcc quad_perm:[2,3,0,1] row_mask:0xf bank_mask:0xf
	v_cndmask_b32_dpp v36, v140, v132, vcc quad_perm:[2,3,0,1] row_mask:0xf bank_mask:0xf
	v_cndmask_b32_dpp v37, v141, v133, vcc quad_perm:[2,3,0,1] row_mask:0xf bank_mask:0xf
	v_cndmask_b32_dpp v38, v142, v134, vcc quad_perm:[2,3,0,1] row_mask:0xf bank_mask:0xf
	v_cndmask_b32_dpp v39, v143, v135, vcc quad_perm:[2,3,0,1] row_mask:0xf bank_mask:0xf
	s_mov_b32 vcc_lo, 0xcccccccc
	s_mov_b32 vcc_hi, 0xcccccccc
	v_cndmask_b32_dpp v48, v128, v136, vcc quad_perm:[2,3,0,1] row_mask:0xf bank_mask:0xf
	v_cndmask_b32_dpp v49, v129, v137, vcc quad_perm:[2,3,0,1] row_mask:0xf bank_mask:0xf
	v_cndmask_b32_dpp v50, v130, v138, vcc quad_perm:[2,3,0,1] row_mask:0xf bank_mask:0xf
	v_cndmask_b32_dpp v51, v131, v139, vcc quad_perm:[2,3,0,1] row_mask:0xf bank_mask:0xf
	v_cndmask_b32_dpp v52, v132, v140, vcc quad_perm:[2,3,0,1] row_mask:0xf bank_mask:0xf
	v_cndmask_b32_dpp v53, v133, v141, vcc quad_perm:[2,3,0,1] row_mask:0xf bank_mask:0xf
	v_cndmask_b32_dpp v54, v134, v142, vcc quad_perm:[2,3,0,1] row_mask:0xf bank_mask:0xf
	v_cndmask_b32_dpp v55, v135, v143, vcc quad_perm:[2,3,0,1] row_mask:0xf bank_mask:0xf
	s_add_u32 s76, s74, 0x0
	s_addc_u32 s77, s75, 0
	global_store_dwordx4 v181, v[32:35], s[76:77]
	s_add_u32 s76, s74, 0x2200
	s_addc_u32 s77, s75, 0
	global_store_dwordx4 v181, v[36:39], s[76:77]
	s_add_u32 s76, s74, 0x4400
	s_addc_u32 s77, s75, 0
	global_store_dwordx4 v181, v[48:51], s[76:77]
	s_add_u32 s76, s74, 0x6600
	s_addc_u32 s77, s75, 0
	global_store_dwordx4 v181, v[52:55], s[76:77]
	s_add_u32 s74, s74, 0x44000
	s_addc_u32 s75, s75, 0
	v_pk_mul_f32 v[64:65], v[64:65], v[174:175] op_sel_hi:[1,0]
	v_pk_mul_f32 v[66:67], v[66:67], v[174:175] op_sel_hi:[1,0]
	v_pk_mul_f32 v[68:69], v[68:69], v[174:175] op_sel_hi:[1,0]
	v_pk_mul_f32 v[70:71], v[70:71], v[174:175] op_sel_hi:[1,0]
	v_pk_mul_f32 v[72:73], v[72:73], v[174:175] op_sel_hi:[1,0]
	v_pk_mul_f32 v[74:75], v[74:75], v[174:175] op_sel_hi:[1,0]
	v_pk_mul_f32 v[76:77], v[76:77], v[174:175] op_sel_hi:[1,0]
	v_pk_mul_f32 v[78:79], v[78:79], v[174:175] op_sel_hi:[1,0]
	v_pk_mul_f32 v[80:81], v[80:81], v[174:175] op_sel_hi:[1,0]
	v_pk_mul_f32 v[82:83], v[82:83], v[174:175] op_sel_hi:[1,0]
	v_pk_mul_f32 v[84:85], v[84:85], v[174:175] op_sel_hi:[1,0]
	v_pk_mul_f32 v[86:87], v[86:87], v[174:175] op_sel_hi:[1,0]
	v_pk_mul_f32 v[88:89], v[88:89], v[174:175] op_sel_hi:[1,0]
	v_pk_mul_f32 v[90:91], v[90:91], v[174:175] op_sel_hi:[1,0]
	v_pk_mul_f32 v[92:93], v[92:93], v[174:175] op_sel_hi:[1,0]
	v_pk_mul_f32 v[94:95], v[94:95], v[174:175] op_sel_hi:[1,0]
	v_pk_mul_f32 v[64:65], v[64:65], v[198:199]
	v_pk_mul_f32 v[66:67], v[66:67], v[200:201]
	v_pk_mul_f32 v[68:69], v[68:69], v[202:203]
	v_pk_mul_f32 v[70:71], v[70:71], v[204:205]
	v_pk_mul_f32 v[72:73], v[72:73], v[206:207]
	v_pk_mul_f32 v[74:75], v[74:75], v[208:209]
	v_pk_mul_f32 v[76:77], v[76:77], v[210:211]
	v_pk_mul_f32 v[78:79], v[78:79], v[212:213]
	v_pk_mul_f32 v[80:81], v[80:81], v[214:215]
	v_pk_mul_f32 v[82:83], v[82:83], v[216:217]
	v_pk_mul_f32 v[84:85], v[84:85], v[218:219]
	v_pk_mul_f32 v[86:87], v[86:87], v[220:221]
	v_pk_mul_f32 v[88:89], v[88:89], v[222:223]
	v_pk_mul_f32 v[90:91], v[90:91], v[224:225]
	v_pk_mul_f32 v[92:93], v[92:93], v[226:227]
	v_pk_mul_f32 v[94:95], v[94:95], v[228:229]
	s_cmp_eq_u32 s37, 0
	s_cbranch_scc1 .Lpe_norope_2_L0
	s_waitcnt vmcnt(4)
	v_pk_mul_f32 v[128:129], v[80:81], v[148:149]
	v_pk_mul_f32 v[164:165], v[80:81], v[230:231]
	v_pk_mul_f32 v[130:131], v[82:83], v[150:151]
	v_pk_mul_f32 v[166:167], v[82:83], v[232:233]
	v_pk_mul_f32 v[132:133], v[84:85], v[152:153]
	v_pk_mul_f32 v[168:169], v[84:85], v[234:235]
	v_pk_mul_f32 v[134:135], v[86:87], v[154:155]
	v_pk_mul_f32 v[170:171], v[86:87], v[236:237]
	v_pk_mul_f32 v[136:137], v[88:89], v[156:157]
	v_pk_mul_f32 v[246:247], v[88:89], v[238:239]
	v_pk_mul_f32 v[138:139], v[90:91], v[158:159]
	v_pk_mul_f32 v[248:249], v[90:91], v[240:241]
	v_pk_mul_f32 v[140:141], v[92:93], v[160:161]
	v_pk_mul_f32 v[250:251], v[92:93], v[242:243]
	v_pk_mul_f32 v[142:143], v[94:95], v[162:163]
	v_pk_mul_f32 v[252:253], v[94:95], v[244:245]
	v_pk_fma_f32 v[80:81], v[64:65], v[148:149], v[164:165]
	v_pk_fma_f32 v[64:65], v[64:65], v[230:231], v[128:129] neg_lo:[0,0,1] neg_hi:[0,0,1]
	v_pk_fma_f32 v[82:83], v[66:67], v[150:151], v[166:167]
	v_pk_fma_f32 v[66:67], v[66:67], v[232:233], v[130:131] neg_lo:[0,0,1] neg_hi:[0,0,1]
	v_pk_fma_f32 v[84:85], v[68:69], v[152:153], v[168:169]
	v_pk_fma_f32 v[68:69], v[68:69], v[234:235], v[132:133] neg_lo:[0,0,1] neg_hi:[0,0,1]
	v_pk_fma_f32 v[86:87], v[70:71], v[154:155], v[170:171]
	v_pk_fma_f32 v[70:71], v[70:71], v[236:237], v[134:135] neg_lo:[0,0,1] neg_hi:[0,0,1]
	v_pk_fma_f32 v[88:89], v[72:73], v[156:157], v[246:247]
	v_pk_fma_f32 v[72:73], v[72:73], v[238:239], v[136:137] neg_lo:[0,0,1] neg_hi:[0,0,1]
	v_pk_fma_f32 v[90:91], v[74:75], v[158:159], v[248:249]
	v_pk_fma_f32 v[74:75], v[74:75], v[240:241], v[138:139] neg_lo:[0,0,1] neg_hi:[0,0,1]
	v_pk_fma_f32 v[92:93], v[76:77], v[160:161], v[250:251]
	v_pk_fma_f32 v[76:77], v[76:77], v[242:243], v[140:141] neg_lo:[0,0,1] neg_hi:[0,0,1]
	v_pk_fma_f32 v[94:95], v[78:79], v[162:163], v[252:253]
	v_pk_fma_f32 v[78:79], v[78:79], v[244:245], v[142:143] neg_lo:[0,0,1] neg_hi:[0,0,1]
	s_add_u32 s96, s96, 0x1000
	s_addc_u32 s97, s97, 0
	s_add_u32 s100, s100, 0x1000
	s_addc_u32 s101, s101, 0
	global_load_dwordx4 v[230:233], v180, s[96:97] offset:0
	global_load_dwordx4 v[234:237], v180, s[96:97] offset:32
	global_load_dwordx4 v[238:241], v180, s[96:97] offset:64
	global_load_dwordx4 v[242:245], v180, s[96:97] offset:96
	global_load_dwordx4 v[148:151], v180, s[100:101] offset:0
	global_load_dwordx4 v[152:155], v180, s[100:101] offset:32
	global_load_dwordx4 v[156:159], v180, s[100:101] offset:64
	global_load_dwordx4 v[160:163], v180, s[100:101] offset:96
.Lpe_norope_2_L0:
	v_cvt_pk_bf16_f32 v64, v64, v65
	v_cvt_pk_bf16_f32 v65, v66, v67
	v_cvt_pk_bf16_f32 v66, v68, v69
	v_cvt_pk_bf16_f32 v67, v70, v71
	v_cvt_pk_bf16_f32 v68, v72, v73
	v_cvt_pk_bf16_f32 v69, v74, v75
	v_cvt_pk_bf16_f32 v70, v76, v77
	v_cvt_pk_bf16_f32 v71, v78, v79
	v_cvt_pk_bf16_f32 v80, v80, v81
	v_cvt_pk_bf16_f32 v81, v82, v83
	v_cvt_pk_bf16_f32 v82, v84, v85
	v_cvt_pk_bf16_f32 v83, v86, v87
	v_cvt_pk_bf16_f32 v84, v88, v89
	v_cvt_pk_bf16_f32 v85, v90, v91
	v_cvt_pk_bf16_f32 v86, v92, v93
	v_cvt_pk_bf16_f32 v87, v94, v95
	v_permlane32_swap_b32_e32 v64, v66
	v_permlane32_swap_b32_e32 v65, v67
	v_permlane32_swap_b32_e32 v68, v70
	v_permlane32_swap_b32_e32 v69, v71
	v_permlane32_swap_b32_e32 v80, v82
	v_permlane32_swap_b32_e32 v81, v83
	v_permlane32_swap_b32_e32 v84, v86
	v_permlane32_swap_b32_e32 v85, v87
	s_nop 1
	s_mov_b32 vcc_lo, 0x55555555
	s_mov_b32 vcc_hi, 0x55555555
	v_cndmask_b32_dpp v128, v68, v64, vcc quad_perm:[1,0,3,2] row_mask:0xf bank_mask:0xf
	v_cndmask_b32_dpp v129, v69, v65, vcc quad_perm:[1,0,3,2] row_mask:0xf bank_mask:0xf
	v_cndmask_b32_dpp v130, v70, v66, vcc quad_perm:[1,0,3,2] row_mask:0xf bank_mask:0xf
	v_cndmask_b32_dpp v131, v71, v67, vcc quad_perm:[1,0,3,2] row_mask:0xf bank_mask:0xf
	v_cndmask_b32_dpp v136, v84, v80, vcc quad_perm:[1,0,3,2] row_mask:0xf bank_mask:0xf
	v_cndmask_b32_dpp v137, v85, v81, vcc quad_perm:[1,0,3,2] row_mask:0xf bank_mask:0xf
	v_cndmask_b32_dpp v138, v86, v82, vcc quad_perm:[1,0,3,2] row_mask:0xf bank_mask:0xf
	v_cndmask_b32_dpp v139, v87, v83, vcc quad_perm:[1,0,3,2] row_mask:0xf bank_mask:0xf
	s_mov_b32 vcc_lo, 0xaaaaaaaa
	s_mov_b32 vcc_hi, 0xaaaaaaaa
	v_cndmask_b32_dpp v132, v64, v68, vcc quad_perm:[1,0,3,2] row_mask:0xf bank_mask:0xf
	v_cndmask_b32_dpp v133, v65, v69, vcc quad_perm:[1,0,3,2] row_mask:0xf bank_mask:0xf
	v_cndmask_b32_dpp v134, v66, v70, vcc quad_perm:[1,0,3,2] row_mask:0xf bank_mask:0xf
	v_cndmask_b32_dpp v135, v67, v71, vcc quad_perm:[1,0,3,2] row_mask:0xf bank_mask:0xf
	v_cndmask_b32_dpp v140, v80, v84, vcc quad_perm:[1,0,3,2] row_mask:0xf bank_mask:0xf
	v_cndmask_b32_dpp v141, v81, v85, vcc quad_perm:[1,0,3,2] row_mask:0xf bank_mask:0xf
	v_cndmask_b32_dpp v142, v82, v86, vcc quad_perm:[1,0,3,2] row_mask:0xf bank_mask:0xf
	v_cndmask_b32_dpp v143, v83, v87, vcc quad_perm:[1,0,3,2] row_mask:0xf bank_mask:0xf
	s_nop 1
	s_mov_b32 vcc_lo, 0x33333333
	s_mov_b32 vcc_hi, 0x33333333
	v_cndmask_b32_dpp v64, v136, v128, vcc quad_perm:[2,3,0,1] row_mask:0xf bank_mask:0xf
	v_cndmask_b32_dpp v65, v137, v129, vcc quad_perm:[2,3,0,1] row_mask:0xf bank_mask:0xf
	v_cndmask_b32_dpp v66, v138, v130, vcc quad_perm:[2,3,0,1] row_mask:0xf bank_mask:0xf
	v_cndmask_b32_dpp v67, v139, v131, vcc quad_perm:[2,3,0,1] row_mask:0xf bank_mask:0xf
	v_cndmask_b32_dpp v68, v140, v132, vcc quad_perm:[2,3,0,1] row_mask:0xf bank_mask:0xf
	v_cndmask_b32_dpp v69, v141, v133, vcc quad_perm:[2,3,0,1] row_mask:0xf bank_mask:0xf
	v_cndmask_b32_dpp v70, v142, v134, vcc quad_perm:[2,3,0,1] row_mask:0xf bank_mask:0xf
	v_cndmask_b32_dpp v71, v143, v135, vcc quad_perm:[2,3,0,1] row_mask:0xf bank_mask:0xf
	s_mov_b32 vcc_lo, 0xcccccccc
	s_mov_b32 vcc_hi, 0xcccccccc
	v_cndmask_b32_dpp v80, v128, v136, vcc quad_perm:[2,3,0,1] row_mask:0xf bank_mask:0xf
	v_cndmask_b32_dpp v81, v129, v137, vcc quad_perm:[2,3,0,1] row_mask:0xf bank_mask:0xf
	v_cndmask_b32_dpp v82, v130, v138, vcc quad_perm:[2,3,0,1] row_mask:0xf bank_mask:0xf
	v_cndmask_b32_dpp v83, v131, v139, vcc quad_perm:[2,3,0,1] row_mask:0xf bank_mask:0xf
	v_cndmask_b32_dpp v84, v132, v140, vcc quad_perm:[2,3,0,1] row_mask:0xf bank_mask:0xf
	v_cndmask_b32_dpp v85, v133, v141, vcc quad_perm:[2,3,0,1] row_mask:0xf bank_mask:0xf
	v_cndmask_b32_dpp v86, v134, v142, vcc quad_perm:[2,3,0,1] row_mask:0xf bank_mask:0xf
	v_cndmask_b32_dpp v87, v135, v143, vcc quad_perm:[2,3,0,1] row_mask:0xf bank_mask:0xf
	s_add_u32 s76, s74, 0x0
	s_addc_u32 s77, s75, 0
	global_store_dwordx4 v181, v[64:67], s[76:77]
	s_add_u32 s76, s74, 0x2200
	s_addc_u32 s77, s75, 0
	global_store_dwordx4 v181, v[68:71], s[76:77]
	s_add_u32 s76, s74, 0x4400
	s_addc_u32 s77, s75, 0
	global_store_dwordx4 v181, v[80:83], s[76:77]
	s_add_u32 s76, s74, 0x6600
	s_addc_u32 s77, s75, 0
	global_store_dwordx4 v181, v[84:87], s[76:77]
	s_add_u32 s74, s74, 0x44000
	s_addc_u32 s75, s75, 0
	v_pk_mul_f32 v[96:97], v[96:97], v[174:175] op_sel:[0,1] op_sel_hi:[1,1]
	v_pk_mul_f32 v[98:99], v[98:99], v[174:175] op_sel:[0,1] op_sel_hi:[1,1]
	v_pk_mul_f32 v[100:101], v[100:101], v[174:175] op_sel:[0,1] op_sel_hi:[1,1]
	v_pk_mul_f32 v[102:103], v[102:103], v[174:175] op_sel:[0,1] op_sel_hi:[1,1]
	v_pk_mul_f32 v[104:105], v[104:105], v[174:175] op_sel:[0,1] op_sel_hi:[1,1]
	v_pk_mul_f32 v[106:107], v[106:107], v[174:175] op_sel:[0,1] op_sel_hi:[1,1]
	v_pk_mul_f32 v[108:109], v[108:109], v[174:175] op_sel:[0,1] op_sel_hi:[1,1]
	v_pk_mul_f32 v[110:111], v[110:111], v[174:175] op_sel:[0,1] op_sel_hi:[1,1]
	v_pk_mul_f32 v[112:113], v[112:113], v[174:175] op_sel:[0,1] op_sel_hi:[1,1]
	v_pk_mul_f32 v[114:115], v[114:115], v[174:175] op_sel:[0,1] op_sel_hi:[1,1]
	v_pk_mul_f32 v[116:117], v[116:117], v[174:175] op_sel:[0,1] op_sel_hi:[1,1]
	v_pk_mul_f32 v[118:119], v[118:119], v[174:175] op_sel:[0,1] op_sel_hi:[1,1]
	v_pk_mul_f32 v[120:121], v[120:121], v[174:175] op_sel:[0,1] op_sel_hi:[1,1]
	v_pk_mul_f32 v[122:123], v[122:123], v[174:175] op_sel:[0,1] op_sel_hi:[1,1]
	v_pk_mul_f32 v[124:125], v[124:125], v[174:175] op_sel:[0,1] op_sel_hi:[1,1]
	v_pk_mul_f32 v[126:127], v[126:127], v[174:175] op_sel:[0,1] op_sel_hi:[1,1]
	v_pk_mul_f32 v[96:97], v[96:97], v[198:199]
	v_pk_mul_f32 v[98:99], v[98:99], v[200:201]
	v_pk_mul_f32 v[100:101], v[100:101], v[202:203]
	v_pk_mul_f32 v[102:103], v[102:103], v[204:205]
	v_pk_mul_f32 v[104:105], v[104:105], v[206:207]
	v_pk_mul_f32 v[106:107], v[106:107], v[208:209]
	v_pk_mul_f32 v[108:109], v[108:109], v[210:211]
	v_pk_mul_f32 v[110:111], v[110:111], v[212:213]
	v_pk_mul_f32 v[112:113], v[112:113], v[214:215]
	v_pk_mul_f32 v[114:115], v[114:115], v[216:217]
	v_pk_mul_f32 v[116:117], v[116:117], v[218:219]
	v_pk_mul_f32 v[118:119], v[118:119], v[220:221]
	v_pk_mul_f32 v[120:121], v[120:121], v[222:223]
	v_pk_mul_f32 v[122:123], v[122:123], v[224:225]
	v_pk_mul_f32 v[124:125], v[124:125], v[226:227]
	v_pk_mul_f32 v[126:127], v[126:127], v[228:229]
	s_cmp_eq_u32 s37, 0
	s_cbranch_scc1 .Lpe_norope_3_L0
	s_waitcnt vmcnt(4)
	v_pk_mul_f32 v[128:129], v[112:113], v[148:149]
	v_pk_mul_f32 v[164:165], v[112:113], v[230:231]
	v_pk_mul_f32 v[130:131], v[114:115], v[150:151]
	v_pk_mul_f32 v[166:167], v[114:115], v[232:233]
	v_pk_mul_f32 v[132:133], v[116:117], v[152:153]
	v_pk_mul_f32 v[168:169], v[116:117], v[234:235]
	v_pk_mul_f32 v[134:135], v[118:119], v[154:155]
	v_pk_mul_f32 v[170:171], v[118:119], v[236:237]
	v_pk_mul_f32 v[136:137], v[120:121], v[156:157]
	v_pk_mul_f32 v[246:247], v[120:121], v[238:239]
	v_pk_mul_f32 v[138:139], v[122:123], v[158:159]
	v_pk_mul_f32 v[248:249], v[122:123], v[240:241]
	v_pk_mul_f32 v[140:141], v[124:125], v[160:161]
	v_pk_mul_f32 v[250:251], v[124:125], v[242:243]
	v_pk_mul_f32 v[142:143], v[126:127], v[162:163]
	v_pk_mul_f32 v[252:253], v[126:127], v[244:245]
	v_pk_fma_f32 v[112:113], v[96:97], v[148:149], v[164:165]
	v_pk_fma_f32 v[96:97], v[96:97], v[230:231], v[128:129] neg_lo:[0,0,1] neg_hi:[0,0,1]
	v_pk_fma_f32 v[114:115], v[98:99], v[150:151], v[166:167]
	v_pk_fma_f32 v[98:99], v[98:99], v[232:233], v[130:131] neg_lo:[0,0,1] neg_hi:[0,0,1]
	v_pk_fma_f32 v[116:117], v[100:101], v[152:153], v[168:169]
	v_pk_fma_f32 v[100:101], v[100:101], v[234:235], v[132:133] neg_lo:[0,0,1] neg_hi:[0,0,1]
	v_pk_fma_f32 v[118:119], v[102:103], v[154:155], v[170:171]
	v_pk_fma_f32 v[102:103], v[102:103], v[236:237], v[134:135] neg_lo:[0,0,1] neg_hi:[0,0,1]
	v_pk_fma_f32 v[120:121], v[104:105], v[156:157], v[246:247]
	v_pk_fma_f32 v[104:105], v[104:105], v[238:239], v[136:137] neg_lo:[0,0,1] neg_hi:[0,0,1]
	v_pk_fma_f32 v[122:123], v[106:107], v[158:159], v[248:249]
	v_pk_fma_f32 v[106:107], v[106:107], v[240:241], v[138:139] neg_lo:[0,0,1] neg_hi:[0,0,1]
	v_pk_fma_f32 v[124:125], v[108:109], v[160:161], v[250:251]
	v_pk_fma_f32 v[108:109], v[108:109], v[242:243], v[140:141] neg_lo:[0,0,1] neg_hi:[0,0,1]
	v_pk_fma_f32 v[126:127], v[110:111], v[162:163], v[252:253]
	v_pk_fma_f32 v[110:111], v[110:111], v[244:245], v[142:143] neg_lo:[0,0,1] neg_hi:[0,0,1]
.Lpe_norope_3_L0:
	v_cvt_pk_bf16_f32 v96, v96, v97
	v_cvt_pk_bf16_f32 v97, v98, v99
	v_cvt_pk_bf16_f32 v98, v100, v101
	v_cvt_pk_bf16_f32 v99, v102, v103
	v_cvt_pk_bf16_f32 v100, v104, v105
	v_cvt_pk_bf16_f32 v101, v106, v107
	v_cvt_pk_bf16_f32 v102, v108, v109
	v_cvt_pk_bf16_f32 v103, v110, v111
	v_cvt_pk_bf16_f32 v112, v112, v113
	v_cvt_pk_bf16_f32 v113, v114, v115
	v_cvt_pk_bf16_f32 v114, v116, v117
	v_cvt_pk_bf16_f32 v115, v118, v119
	v_cvt_pk_bf16_f32 v116, v120, v121
	v_cvt_pk_bf16_f32 v117, v122, v123
	v_cvt_pk_bf16_f32 v118, v124, v125
	v_cvt_pk_bf16_f32 v119, v126, v127
	v_permlane32_swap_b32_e32 v96, v98
	v_permlane32_swap_b32_e32 v97, v99
	v_permlane32_swap_b32_e32 v100, v102
	v_permlane32_swap_b32_e32 v101, v103
	v_permlane32_swap_b32_e32 v112, v114
	v_permlane32_swap_b32_e32 v113, v115
	v_permlane32_swap_b32_e32 v116, v118
	v_permlane32_swap_b32_e32 v117, v119
	s_nop 1
	s_mov_b32 vcc_lo, 0x55555555
	s_mov_b32 vcc_hi, 0x55555555
	v_cndmask_b32_dpp v128, v100, v96, vcc quad_perm:[1,0,3,2] row_mask:0xf bank_mask:0xf
	v_cndmask_b32_dpp v129, v101, v97, vcc quad_perm:[1,0,3,2] row_mask:0xf bank_mask:0xf
	v_cndmask_b32_dpp v130, v102, v98, vcc quad_perm:[1,0,3,2] row_mask:0xf bank_mask:0xf
	v_cndmask_b32_dpp v131, v103, v99, vcc quad_perm:[1,0,3,2] row_mask:0xf bank_mask:0xf
	v_cndmask_b32_dpp v136, v116, v112, vcc quad_perm:[1,0,3,2] row_mask:0xf bank_mask:0xf
	v_cndmask_b32_dpp v137, v117, v113, vcc quad_perm:[1,0,3,2] row_mask:0xf bank_mask:0xf
	v_cndmask_b32_dpp v138, v118, v114, vcc quad_perm:[1,0,3,2] row_mask:0xf bank_mask:0xf
	v_cndmask_b32_dpp v139, v119, v115, vcc quad_perm:[1,0,3,2] row_mask:0xf bank_mask:0xf
	s_mov_b32 vcc_lo, 0xaaaaaaaa
	s_mov_b32 vcc_hi, 0xaaaaaaaa
	v_cndmask_b32_dpp v132, v96, v100, vcc quad_perm:[1,0,3,2] row_mask:0xf bank_mask:0xf
	v_cndmask_b32_dpp v133, v97, v101, vcc quad_perm:[1,0,3,2] row_mask:0xf bank_mask:0xf
	v_cndmask_b32_dpp v134, v98, v102, vcc quad_perm:[1,0,3,2] row_mask:0xf bank_mask:0xf
	v_cndmask_b32_dpp v135, v99, v103, vcc quad_perm:[1,0,3,2] row_mask:0xf bank_mask:0xf
	v_cndmask_b32_dpp v140, v112, v116, vcc quad_perm:[1,0,3,2] row_mask:0xf bank_mask:0xf
	v_cndmask_b32_dpp v141, v113, v117, vcc quad_perm:[1,0,3,2] row_mask:0xf bank_mask:0xf
	v_cndmask_b32_dpp v142, v114, v118, vcc quad_perm:[1,0,3,2] row_mask:0xf bank_mask:0xf
	v_cndmask_b32_dpp v143, v115, v119, vcc quad_perm:[1,0,3,2] row_mask:0xf bank_mask:0xf
	s_nop 1
	s_mov_b32 vcc_lo, 0x33333333
	s_mov_b32 vcc_hi, 0x33333333
	v_cndmask_b32_dpp v96, v136, v128, vcc quad_perm:[2,3,0,1] row_mask:0xf bank_mask:0xf
	v_cndmask_b32_dpp v97, v137, v129, vcc quad_perm:[2,3,0,1] row_mask:0xf bank_mask:0xf
	v_cndmask_b32_dpp v98, v138, v130, vcc quad_perm:[2,3,0,1] row_mask:0xf bank_mask:0xf
	v_cndmask_b32_dpp v99, v139, v131, vcc quad_perm:[2,3,0,1] row_mask:0xf bank_mask:0xf
	v_cndmask_b32_dpp v100, v140, v132, vcc quad_perm:[2,3,0,1] row_mask:0xf bank_mask:0xf
	v_cndmask_b32_dpp v101, v141, v133, vcc quad_perm:[2,3,0,1] row_mask:0xf bank_mask:0xf
	v_cndmask_b32_dpp v102, v142, v134, vcc quad_perm:[2,3,0,1] row_mask:0xf bank_mask:0xf
	v_cndmask_b32_dpp v103, v143, v135, vcc quad_perm:[2,3,0,1] row_mask:0xf bank_mask:0xf
	s_mov_b32 vcc_lo, 0xcccccccc
	s_mov_b32 vcc_hi, 0xcccccccc
	v_cndmask_b32_dpp v112, v128, v136, vcc quad_perm:[2,3,0,1] row_mask:0xf bank_mask:0xf
	v_cndmask_b32_dpp v113, v129, v137, vcc quad_perm:[2,3,0,1] row_mask:0xf bank_mask:0xf
	v_cndmask_b32_dpp v114, v130, v138, vcc quad_perm:[2,3,0,1] row_mask:0xf bank_mask:0xf
	v_cndmask_b32_dpp v115, v131, v139, vcc quad_perm:[2,3,0,1] row_mask:0xf bank_mask:0xf
	v_cndmask_b32_dpp v116, v132, v140, vcc quad_perm:[2,3,0,1] row_mask:0xf bank_mask:0xf
	v_cndmask_b32_dpp v117, v133, v141, vcc quad_perm:[2,3,0,1] row_mask:0xf bank_mask:0xf
	v_cndmask_b32_dpp v118, v134, v142, vcc quad_perm:[2,3,0,1] row_mask:0xf bank_mask:0xf
	v_cndmask_b32_dpp v119, v135, v143, vcc quad_perm:[2,3,0,1] row_mask:0xf bank_mask:0xf
	s_add_u32 s76, s74, 0x0
	s_addc_u32 s77, s75, 0
	global_store_dwordx4 v181, v[96:99], s[76:77]
	s_add_u32 s76, s74, 0x2200
	s_addc_u32 s77, s75, 0
	global_store_dwordx4 v181, v[100:103], s[76:77]
	s_add_u32 s76, s74, 0x4400
	s_addc_u32 s77, s75, 0
	global_store_dwordx4 v181, v[112:115], s[76:77]
	s_add_u32 s76, s74, 0x6600
	s_addc_u32 s77, s75, 0
	global_store_dwordx4 v181, v[116:119], s[76:77]
	s_branch .Lpe_ret_L0
.Lpe_gates_L0:
	s_lshl_b32 s35, s98, 11
	s_add_u32 s35, s35, s30
	s_sub_u32 s35, s35, 0x900
	s_lshl_b32 s35, s35, 2
	v_readlane_b32 s82, v254, 12
	v_readlane_b32 s83, v254, 13
	s_add_u32 s82, s82, s35
	s_addc_u32 s83, s83, 0
	global_load_dwordx4 v[198:201], v146, s[82:83] offset:0
	global_load_dwordx4 v[202:205], v146, s[82:83] offset:32
	global_load_dwordx4 v[206:209], v146, s[82:83] offset:64
	global_load_dwordx4 v[210:213], v146, s[82:83] offset:96
	global_load_dwordx4 v[214:217], v146, s[82:83] offset:128
	global_load_dwordx4 v[218:221], v146, s[82:83] offset:160
	global_load_dwordx4 v[222:225], v146, s[82:83] offset:192
	global_load_dwordx4 v[226:229], v146, s[82:83] offset:224
	s_waitcnt vmcnt(8)
	v_mov_b32_e32 v197, 0x358637bd
	v_pk_add_f32 v[128:129], v[128:129], v[130:131]
	v_pk_add_f32 v[132:133], v[132:133], v[134:135]
	v_pk_add_f32 v[136:137], v[136:137], v[138:139]
	v_pk_add_f32 v[140:141], v[140:141], v[142:143]
	v_pk_add_f32 v[164:165], v[164:165], v[166:167]
	v_pk_add_f32 v[168:169], v[168:169], v[170:171]
	v_pk_add_f32 v[246:247], v[246:247], v[248:249]
	v_pk_add_f32 v[250:251], v[250:251], v[252:253]
	v_pk_add_f32 v[128:129], v[128:129], v[132:133]
	v_pk_add_f32 v[136:137], v[136:137], v[140:141]
	v_pk_add_f32 v[164:165], v[164:165], v[168:169]
	v_pk_add_f32 v[246:247], v[246:247], v[250:251]
	v_add_f32_e32 v128, v128, v129
	v_add_f32_e32 v136, v136, v137
	v_add_f32_e32 v164, v164, v165
	v_add_f32_e32 v246, v246, v247
	v_fmamk_f32 v128, v128, 0x3a800000, v197
	v_fmamk_f32 v136, v136, 0x3a800000, v197
	v_fmamk_f32 v164, v164, 0x3a800000, v197
	v_fmamk_f32 v246, v246, 0x3a800000, v197
	v_rsq_f32_e32 v172, v128
	v_rsq_f32_e32 v173, v136
	v_rsq_f32_e32 v174, v164
	v_rsq_f32_e32 v175, v246
	s_nop 0
	s_add_u32 s76, s99, s90
	s_cmp_lt_u32 s76, 0x440
	s_cselect_b32 s80, 1, 0
	s_cselect_b32 s83, 0x200000, 0
	s_lshl_b32 s76, s24, 19
	s_lshl_b32 s77, s26, 16
	s_add_u32 s76, s76, s77
	s_and_b32 s77, s24, 7
	s_lshl_b32 s77, s77, 8
	s_add_u32 s76, s76, s77
	s_add_u32 s78, s72, 0xa120000
	s_addc_u32 s79, s73, 0
	s_add_u32 s78, s78, s76
	s_addc_u32 s79, s79, 0
	s_lshl_b32 s76, s25, 19
	s_add_u32 s76, s76, s83
	s_add_u32 s76, s76, s77
	s_lshl_b32 s77, s26, 16
	s_add_u32 s76, s76, s77
	s_add_u32 s82, s72, 0x0
	s_addc_u32 s83, s73, 0
	s_add_u32 s82, s82, s76
	s_addc_u32 s83, s83, 0
	s_lshl_b32 s76, s26, 12
	s_mov_b32 m0, s76
	s_nop 0
	global_load_lds_dwordx4 v145, s[78:79]
	s_add_u32 s78, s78, 0x4000
	s_addc_u32 s79, s79, 0
	s_add_u32 s76, s76, 0x400
	s_mov_b32 m0, s76
	s_nop 0
	global_load_lds_dwordx4 v185, s[78:79]
	s_add_u32 s78, s78, 0x4000
	s_addc_u32 s79, s79, 0
	s_add_u32 s76, s76, 0x400
	s_mov_b32 m0, s76
	s_nop 0
	global_load_lds_dwordx4 v145, s[78:79]
	s_add_u32 s78, s78, 0x4000
	s_addc_u32 s79, s79, 0
	s_add_u32 s76, s76, 0x400
	s_mov_b32 m0, s76
	s_nop 0
	global_load_lds_dwordx4 v185, s[78:79]
	s_add_u32 s78, s78, 0x4000
	s_addc_u32 s79, s79, 0
	s_add_u32 s76, s76, 0x400
	s_add_u32 s76, s76, 0x7000
	s_mov_b32 m0, s76
	s_nop 0
	global_load_lds_dwordx4 v145, s[82:83]
	s_add_u32 s82, s82, 0x4000
	s_addc_u32 s83, s83, 0
	s_add_u32 s76, s76, 0x400
	s_mov_b32 m0, s76
	s_nop 0
	global_load_lds_dwordx4 v185, s[82:83]
	s_add_u32 s82, s82, 0x4000
	s_addc_u32 s83, s83, 0
	s_add_u32 s76, s76, 0x400
	s_mov_b32 m0, s76
	s_nop 0
	global_load_lds_dwordx4 v145, s[82:83]
	s_add_u32 s82, s82, 0x4000
	s_addc_u32 s83, s83, 0
	s_add_u32 s76, s76, 0x400
	s_mov_b32 m0, s76
	s_nop 0
	global_load_lds_dwordx4 v185, s[82:83]
	s_add_u32 s82, s82, 0x4000
	s_addc_u32 s83, s83, 0
	s_add_u32 s76, s76, 0x400
	v_mul_f32_e32 v172, 0xbfb8aa3b, v172
	v_mul_f32_e32 v173, 0xbfb8aa3b, v173
	v_mul_f32_e32 v174, 0xbfb8aa3b, v174
	v_mul_f32_e32 v175, 0xbfb8aa3b, v175
	s_waitcnt vmcnt(8)
	v_mul_f32_e32 v198, 0xbfb8aa3b, v198
	v_mul_f32_e32 v199, 0xbfb8aa3b, v199
	v_mul_f32_e32 v200, 0xbfb8aa3b, v200
	v_mul_f32_e32 v201, 0xbfb8aa3b, v201
	v_mul_f32_e32 v202, 0xbfb8aa3b, v202
	v_mul_f32_e32 v203, 0xbfb8aa3b, v203
	v_mul_f32_e32 v204, 0xbfb8aa3b, v204
	v_mul_f32_e32 v205, 0xbfb8aa3b, v205
	v_mul_f32_e32 v206, 0xbfb8aa3b, v206
	v_mul_f32_e32 v207, 0xbfb8aa3b, v207
	v_mul_f32_e32 v208, 0xbfb8aa3b, v208
	v_mul_f32_e32 v209, 0xbfb8aa3b, v209
	v_mul_f32_e32 v210, 0xbfb8aa3b, v210
	v_mul_f32_e32 v211, 0xbfb8aa3b, v211
	v_mul_f32_e32 v212, 0xbfb8aa3b, v212
	v_mul_f32_e32 v213, 0xbfb8aa3b, v213
	v_mul_f32_e32 v214, 0xbfb8aa3b, v214
	v_mul_f32_e32 v215, 0xbfb8aa3b, v215
	v_mul_f32_e32 v216, 0xbfb8aa3b, v216
	v_mul_f32_e32 v217, 0xbfb8aa3b, v217
	v_mul_f32_e32 v218, 0xbfb8aa3b, v218
	v_mul_f32_e32 v219, 0xbfb8aa3b, v219
	v_mul_f32_e32 v220, 0xbfb8aa3b, v220
	v_mul_f32_e32 v221, 0xbfb8aa3b, v221
	v_mul_f32_e32 v222, 0xbfb8aa3b, v222
	v_mul_f32_e32 v223, 0xbfb8aa3b, v223
	v_mul_f32_e32 v224, 0xbfb8aa3b, v224
	v_mul_f32_e32 v225, 0xbfb8aa3b, v225
	v_mul_f32_e32 v226, 0xbfb8aa3b, v226
	v_mul_f32_e32 v227, 0xbfb8aa3b, v227
	v_mul_f32_e32 v228, 0xbfb8aa3b, v228
	v_mul_f32_e32 v229, 0xbfb8aa3b, v229
	v_pk_fma_f32 v[0:1], v[0:1], v[172:173], v[198:199] op_sel_hi:[1,0,1]
	v_pk_fma_f32 v[2:3], v[2:3], v[172:173], v[200:201] op_sel_hi:[1,0,1]
	v_pk_fma_f32 v[4:5], v[4:5], v[172:173], v[202:203] op_sel_hi:[1,0,1]
	v_pk_fma_f32 v[6:7], v[6:7], v[172:173], v[204:205] op_sel_hi:[1,0,1]
	v_pk_fma_f32 v[8:9], v[8:9], v[172:173], v[206:207] op_sel_hi:[1,0,1]
	v_pk_fma_f32 v[10:11], v[10:11], v[172:173], v[208:209] op_sel_hi:[1,0,1]
	v_pk_fma_f32 v[12:13], v[12:13], v[172:173], v[210:211] op_sel_hi:[1,0,1]
	v_pk_fma_f32 v[14:15], v[14:15], v[172:173], v[212:213] op_sel_hi:[1,0,1]
	v_pk_fma_f32 v[16:17], v[16:17], v[172:173], v[214:215] op_sel_hi:[1,0,1]
	v_pk_fma_f32 v[18:19], v[18:19], v[172:173], v[216:217] op_sel_hi:[1,0,1]
	v_pk_fma_f32 v[20:21], v[20:21], v[172:173], v[218:219] op_sel_hi:[1,0,1]
	v_pk_fma_f32 v[22:23], v[22:23], v[172:173], v[220:221] op_sel_hi:[1,0,1]
	v_pk_fma_f32 v[24:25], v[24:25], v[172:173], v[222:223] op_sel_hi:[1,0,1]
	v_pk_fma_f32 v[26:27], v[26:27], v[172:173], v[224:225] op_sel_hi:[1,0,1]
	v_pk_fma_f32 v[28:29], v[28:29], v[172:173], v[226:227] op_sel_hi:[1,0,1]
	v_pk_fma_f32 v[30:31], v[30:31], v[172:173], v[228:229] op_sel_hi:[1,0,1]
	v_exp_f32_e32 v0, v0
	v_exp_f32_e32 v1, v1
	v_exp_f32_e32 v2, v2
	v_exp_f32_e32 v3, v3
	v_exp_f32_e32 v4, v4
	v_exp_f32_e32 v5, v5
	v_exp_f32_e32 v6, v6
	v_exp_f32_e32 v7, v7
	v_exp_f32_e32 v8, v8
	v_exp_f32_e32 v9, v9
	v_exp_f32_e32 v10, v10
	v_exp_f32_e32 v11, v11
	v_exp_f32_e32 v12, v12
	v_exp_f32_e32 v13, v13
	v_exp_f32_e32 v14, v14
	v_exp_f32_e32 v15, v15
	v_exp_f32_e32 v16, v16
	v_exp_f32_e32 v17, v17
	v_exp_f32_e32 v18, v18
	v_exp_f32_e32 v19, v19
	v_exp_f32_e32 v20, v20
	v_exp_f32_e32 v21, v21
	v_exp_f32_e32 v22, v22
	v_exp_f32_e32 v23, v23
	v_exp_f32_e32 v24, v24
	v_exp_f32_e32 v25, v25
	v_exp_f32_e32 v26, v26
	v_exp_f32_e32 v27, v27
	v_exp_f32_e32 v28, v28
	v_exp_f32_e32 v29, v29
	v_exp_f32_e32 v30, v30
	v_exp_f32_e32 v31, v31
	v_pk_add_f32 v[0:1], v[0:1], 1.0 op_sel_hi:[1,0]
	v_pk_add_f32 v[2:3], v[2:3], 1.0 op_sel_hi:[1,0]
	v_pk_add_f32 v[4:5], v[4:5], 1.0 op_sel_hi:[1,0]
	v_pk_add_f32 v[6:7], v[6:7], 1.0 op_sel_hi:[1,0]
	v_pk_add_f32 v[8:9], v[8:9], 1.0 op_sel_hi:[1,0]
	v_pk_add_f32 v[10:11], v[10:11], 1.0 op_sel_hi:[1,0]
	v_pk_add_f32 v[12:13], v[12:13], 1.0 op_sel_hi:[1,0]
	v_pk_add_f32 v[14:15], v[14:15], 1.0 op_sel_hi:[1,0]
	v_pk_add_f32 v[16:17], v[16:17], 1.0 op_sel_hi:[1,0]
	v_pk_add_f32 v[18:19], v[18:19], 1.0 op_sel_hi:[1,0]
	v_pk_add_f32 v[20:21], v[20:21], 1.0 op_sel_hi:[1,0]
	v_pk_add_f32 v[22:23], v[22:23], 1.0 op_sel_hi:[1,0]
	v_pk_add_f32 v[24:25], v[24:25], 1.0 op_sel_hi:[1,0]
	v_pk_add_f32 v[26:27], v[26:27], 1.0 op_sel_hi:[1,0]
	v_pk_add_f32 v[28:29], v[28:29], 1.0 op_sel_hi:[1,0]
	v_pk_add_f32 v[30:31], v[30:31], 1.0 op_sel_hi:[1,0]
	v_rcp_f32_e32 v0, v0
	v_rcp_f32_e32 v1, v1
	v_rcp_f32_e32 v2, v2
	v_rcp_f32_e32 v3, v3
	v_rcp_f32_e32 v4, v4
	v_rcp_f32_e32 v5, v5
	v_rcp_f32_e32 v6, v6
	v_rcp_f32_e32 v7, v7
	v_rcp_f32_e32 v8, v8
	v_rcp_f32_e32 v9, v9
	v_rcp_f32_e32 v10, v10
	v_rcp_f32_e32 v11, v11
	v_rcp_f32_e32 v12, v12
	v_rcp_f32_e32 v13, v13
	v_rcp_f32_e32 v14, v14
	v_rcp_f32_e32 v15, v15
	v_rcp_f32_e32 v16, v16
	v_rcp_f32_e32 v17, v17
	v_rcp_f32_e32 v18, v18
	v_rcp_f32_e32 v19, v19
	v_rcp_f32_e32 v20, v20
	v_rcp_f32_e32 v21, v21
	v_rcp_f32_e32 v22, v22
	v_rcp_f32_e32 v23, v23
	v_rcp_f32_e32 v24, v24
	v_rcp_f32_e32 v25, v25
	v_rcp_f32_e32 v26, v26
	v_rcp_f32_e32 v27, v27
	v_rcp_f32_e32 v28, v28
	v_rcp_f32_e32 v29, v29
	v_rcp_f32_e32 v30, v30
	v_rcp_f32_e32 v31, v31
	s_nop 0
	v_cvt_pk_bf16_f32 v0, v0, v1
	v_cvt_pk_bf16_f32 v1, v2, v3
	v_cvt_pk_bf16_f32 v2, v4, v5
	v_cvt_pk_bf16_f32 v3, v6, v7
	v_cvt_pk_bf16_f32 v4, v8, v9
	v_cvt_pk_bf16_f32 v5, v10, v11
	v_cvt_pk_bf16_f32 v6, v12, v13
	v_cvt_pk_bf16_f32 v7, v14, v15
	v_cvt_pk_bf16_f32 v16, v16, v17
	v_cvt_pk_bf16_f32 v17, v18, v19
	v_cvt_pk_bf16_f32 v18, v20, v21
	v_cvt_pk_bf16_f32 v19, v22, v23
	v_cvt_pk_bf16_f32 v20, v24, v25
	v_cvt_pk_bf16_f32 v21, v26, v27
	v_cvt_pk_bf16_f32 v22, v28, v29
	v_cvt_pk_bf16_f32 v23, v30, v31
	v_permlane32_swap_b32_e32 v0, v2
	v_permlane32_swap_b32_e32 v1, v3
	v_permlane32_swap_b32_e32 v4, v6
	v_permlane32_swap_b32_e32 v5, v7
	v_permlane32_swap_b32_e32 v16, v18
	v_permlane32_swap_b32_e32 v17, v19
	v_permlane32_swap_b32_e32 v20, v22
	v_permlane32_swap_b32_e32 v21, v23
	s_nop 1
	s_mov_b32 vcc_lo, 0x55555555
	s_mov_b32 vcc_hi, 0x55555555
	v_cndmask_b32_dpp v128, v4, v0, vcc quad_perm:[1,0,3,2] row_mask:0xf bank_mask:0xf
	v_cndmask_b32_dpp v129, v5, v1, vcc quad_perm:[1,0,3,2] row_mask:0xf bank_mask:0xf
	v_cndmask_b32_dpp v130, v6, v2, vcc quad_perm:[1,0,3,2] row_mask:0xf bank_mask:0xf
	v_cndmask_b32_dpp v131, v7, v3, vcc quad_perm:[1,0,3,2] row_mask:0xf bank_mask:0xf
	v_cndmask_b32_dpp v136, v20, v16, vcc quad_perm:[1,0,3,2] row_mask:0xf bank_mask:0xf
	v_cndmask_b32_dpp v137, v21, v17, vcc quad_perm:[1,0,3,2] row_mask:0xf bank_mask:0xf
	v_cndmask_b32_dpp v138, v22, v18, vcc quad_perm:[1,0,3,2] row_mask:0xf bank_mask:0xf
	v_cndmask_b32_dpp v139, v23, v19, vcc quad_perm:[1,0,3,2] row_mask:0xf bank_mask:0xf
	s_mov_b32 vcc_lo, 0xaaaaaaaa
	s_mov_b32 vcc_hi, 0xaaaaaaaa
	v_cndmask_b32_dpp v132, v0, v4, vcc quad_perm:[1,0,3,2] row_mask:0xf bank_mask:0xf
	v_cndmask_b32_dpp v133, v1, v5, vcc quad_perm:[1,0,3,2] row_mask:0xf bank_mask:0xf
	v_cndmask_b32_dpp v134, v2, v6, vcc quad_perm:[1,0,3,2] row_mask:0xf bank_mask:0xf
	v_cndmask_b32_dpp v135, v3, v7, vcc quad_perm:[1,0,3,2] row_mask:0xf bank_mask:0xf
	v_cndmask_b32_dpp v140, v16, v20, vcc quad_perm:[1,0,3,2] row_mask:0xf bank_mask:0xf
	v_cndmask_b32_dpp v141, v17, v21, vcc quad_perm:[1,0,3,2] row_mask:0xf bank_mask:0xf
	v_cndmask_b32_dpp v142, v18, v22, vcc quad_perm:[1,0,3,2] row_mask:0xf bank_mask:0xf
	v_cndmask_b32_dpp v143, v19, v23, vcc quad_perm:[1,0,3,2] row_mask:0xf bank_mask:0xf
	s_nop 1
	s_mov_b32 vcc_lo, 0x33333333
	s_mov_b32 vcc_hi, 0x33333333
	v_cndmask_b32_dpp v0, v136, v128, vcc quad_perm:[2,3,0,1] row_mask:0xf bank_mask:0xf
	v_cndmask_b32_dpp v1, v137, v129, vcc quad_perm:[2,3,0,1] row_mask:0xf bank_mask:0xf
	v_cndmask_b32_dpp v2, v138, v130, vcc quad_perm:[2,3,0,1] row_mask:0xf bank_mask:0xf
	v_cndmask_b32_dpp v3, v139, v131, vcc quad_perm:[2,3,0,1] row_mask:0xf bank_mask:0xf
	v_cndmask_b32_dpp v4, v140, v132, vcc quad_perm:[2,3,0,1] row_mask:0xf bank_mask:0xf
	v_cndmask_b32_dpp v5, v141, v133, vcc quad_perm:[2,3,0,1] row_mask:0xf bank_mask:0xf
	v_cndmask_b32_dpp v6, v142, v134, vcc quad_perm:[2,3,0,1] row_mask:0xf bank_mask:0xf
	v_cndmask_b32_dpp v7, v143, v135, vcc quad_perm:[2,3,0,1] row_mask:0xf bank_mask:0xf
	s_mov_b32 vcc_lo, 0xcccccccc
	s_mov_b32 vcc_hi, 0xcccccccc
	v_cndmask_b32_dpp v16, v128, v136, vcc quad_perm:[2,3,0,1] row_mask:0xf bank_mask:0xf
	v_cndmask_b32_dpp v17, v129, v137, vcc quad_perm:[2,3,0,1] row_mask:0xf bank_mask:0xf
	v_cndmask_b32_dpp v18, v130, v138, vcc quad_perm:[2,3,0,1] row_mask:0xf bank_mask:0xf
	v_cndmask_b32_dpp v19, v131, v139, vcc quad_perm:[2,3,0,1] row_mask:0xf bank_mask:0xf
	v_cndmask_b32_dpp v20, v132, v140, vcc quad_perm:[2,3,0,1] row_mask:0xf bank_mask:0xf
	v_cndmask_b32_dpp v21, v133, v141, vcc quad_perm:[2,3,0,1] row_mask:0xf bank_mask:0xf
	v_cndmask_b32_dpp v22, v134, v142, vcc quad_perm:[2,3,0,1] row_mask:0xf bank_mask:0xf
	v_cndmask_b32_dpp v23, v135, v143, vcc quad_perm:[2,3,0,1] row_mask:0xf bank_mask:0xf
	s_add_u32 s76, s74, 0x0
	s_addc_u32 s77, s75, 0
	global_store_dwordx4 v181, v[0:3], s[76:77]
	s_add_u32 s76, s74, 0x2200
	s_addc_u32 s77, s75, 0
	global_store_dwordx4 v181, v[4:7], s[76:77]
	s_add_u32 s76, s74, 0x4400
	s_addc_u32 s77, s75, 0
	global_store_dwordx4 v181, v[16:19], s[76:77]
	s_add_u32 s76, s74, 0x6600
	s_addc_u32 s77, s75, 0
	global_store_dwordx4 v181, v[20:23], s[76:77]
	s_add_u32 s74, s74, 0x44000
	s_addc_u32 s75, s75, 0
	v_pk_fma_f32 v[32:33], v[32:33], v[172:173], v[198:199] op_sel:[0,1,0] op_sel_hi:[1,1,1]
	v_pk_fma_f32 v[34:35], v[34:35], v[172:173], v[200:201] op_sel:[0,1,0] op_sel_hi:[1,1,1]
	v_pk_fma_f32 v[36:37], v[36:37], v[172:173], v[202:203] op_sel:[0,1,0] op_sel_hi:[1,1,1]
	v_pk_fma_f32 v[38:39], v[38:39], v[172:173], v[204:205] op_sel:[0,1,0] op_sel_hi:[1,1,1]
	v_pk_fma_f32 v[40:41], v[40:41], v[172:173], v[206:207] op_sel:[0,1,0] op_sel_hi:[1,1,1]
	v_pk_fma_f32 v[42:43], v[42:43], v[172:173], v[208:209] op_sel:[0,1,0] op_sel_hi:[1,1,1]
	v_pk_fma_f32 v[44:45], v[44:45], v[172:173], v[210:211] op_sel:[0,1,0] op_sel_hi:[1,1,1]
	v_pk_fma_f32 v[46:47], v[46:47], v[172:173], v[212:213] op_sel:[0,1,0] op_sel_hi:[1,1,1]
	v_pk_fma_f32 v[48:49], v[48:49], v[172:173], v[214:215] op_sel:[0,1,0] op_sel_hi:[1,1,1]
	v_pk_fma_f32 v[50:51], v[50:51], v[172:173], v[216:217] op_sel:[0,1,0] op_sel_hi:[1,1,1]
	v_pk_fma_f32 v[52:53], v[52:53], v[172:173], v[218:219] op_sel:[0,1,0] op_sel_hi:[1,1,1]
	v_pk_fma_f32 v[54:55], v[54:55], v[172:173], v[220:221] op_sel:[0,1,0] op_sel_hi:[1,1,1]
	v_pk_fma_f32 v[56:57], v[56:57], v[172:173], v[222:223] op_sel:[0,1,0] op_sel_hi:[1,1,1]
	v_pk_fma_f32 v[58:59], v[58:59], v[172:173], v[224:225] op_sel:[0,1,0] op_sel_hi:[1,1,1]
	v_pk_fma_f32 v[60:61], v[60:61], v[172:173], v[226:227] op_sel:[0,1,0] op_sel_hi:[1,1,1]
	v_pk_fma_f32 v[62:63], v[62:63], v[172:173], v[228:229] op_sel:[0,1,0] op_sel_hi:[1,1,1]
	v_exp_f32_e32 v32, v32
	v_exp_f32_e32 v33, v33
	v_exp_f32_e32 v34, v34
	v_exp_f32_e32 v35, v35
	v_exp_f32_e32 v36, v36
	v_exp_f32_e32 v37, v37
	v_exp_f32_e32 v38, v38
	v_exp_f32_e32 v39, v39
	v_exp_f32_e32 v40, v40
	v_exp_f32_e32 v41, v41
	v_exp_f32_e32 v42, v42
	v_exp_f32_e32 v43, v43
	v_exp_f32_e32 v44, v44
	v_exp_f32_e32 v45, v45
	v_exp_f32_e32 v46, v46
	v_exp_f32_e32 v47, v47
	v_exp_f32_e32 v48, v48
	v_exp_f32_e32 v49, v49
	v_exp_f32_e32 v50, v50
	v_exp_f32_e32 v51, v51
	v_exp_f32_e32 v52, v52
	v_exp_f32_e32 v53, v53
	v_exp_f32_e32 v54, v54
	v_exp_f32_e32 v55, v55
	v_exp_f32_e32 v56, v56
	v_exp_f32_e32 v57, v57
	v_exp_f32_e32 v58, v58
	v_exp_f32_e32 v59, v59
	v_exp_f32_e32 v60, v60
	v_exp_f32_e32 v61, v61
	v_exp_f32_e32 v62, v62
	v_exp_f32_e32 v63, v63
	v_pk_add_f32 v[32:33], v[32:33], 1.0 op_sel_hi:[1,0]
	v_pk_add_f32 v[34:35], v[34:35], 1.0 op_sel_hi:[1,0]
	v_pk_add_f32 v[36:37], v[36:37], 1.0 op_sel_hi:[1,0]
	v_pk_add_f32 v[38:39], v[38:39], 1.0 op_sel_hi:[1,0]
	v_pk_add_f32 v[40:41], v[40:41], 1.0 op_sel_hi:[1,0]
	v_pk_add_f32 v[42:43], v[42:43], 1.0 op_sel_hi:[1,0]
	v_pk_add_f32 v[44:45], v[44:45], 1.0 op_sel_hi:[1,0]
	v_pk_add_f32 v[46:47], v[46:47], 1.0 op_sel_hi:[1,0]
	v_pk_add_f32 v[48:49], v[48:49], 1.0 op_sel_hi:[1,0]
	v_pk_add_f32 v[50:51], v[50:51], 1.0 op_sel_hi:[1,0]
	v_pk_add_f32 v[52:53], v[52:53], 1.0 op_sel_hi:[1,0]
	v_pk_add_f32 v[54:55], v[54:55], 1.0 op_sel_hi:[1,0]
	v_pk_add_f32 v[56:57], v[56:57], 1.0 op_sel_hi:[1,0]
	v_pk_add_f32 v[58:59], v[58:59], 1.0 op_sel_hi:[1,0]
	v_pk_add_f32 v[60:61], v[60:61], 1.0 op_sel_hi:[1,0]
	v_pk_add_f32 v[62:63], v[62:63], 1.0 op_sel_hi:[1,0]
	v_rcp_f32_e32 v32, v32
	v_rcp_f32_e32 v33, v33
	v_rcp_f32_e32 v34, v34
	v_rcp_f32_e32 v35, v35
	v_rcp_f32_e32 v36, v36
	v_rcp_f32_e32 v37, v37
	v_rcp_f32_e32 v38, v38
	v_rcp_f32_e32 v39, v39
	v_rcp_f32_e32 v40, v40
	v_rcp_f32_e32 v41, v41
	v_rcp_f32_e32 v42, v42
	v_rcp_f32_e32 v43, v43
	v_rcp_f32_e32 v44, v44
	v_rcp_f32_e32 v45, v45
	v_rcp_f32_e32 v46, v46
	v_rcp_f32_e32 v47, v47
	v_rcp_f32_e32 v48, v48
	v_rcp_f32_e32 v49, v49
	v_rcp_f32_e32 v50, v50
	v_rcp_f32_e32 v51, v51
	v_rcp_f32_e32 v52, v52
	v_rcp_f32_e32 v53, v53
	v_rcp_f32_e32 v54, v54
	v_rcp_f32_e32 v55, v55
	v_rcp_f32_e32 v56, v56
	v_rcp_f32_e32 v57, v57
	v_rcp_f32_e32 v58, v58
	v_rcp_f32_e32 v59, v59
	v_rcp_f32_e32 v60, v60
	v_rcp_f32_e32 v61, v61
	v_rcp_f32_e32 v62, v62
	v_rcp_f32_e32 v63, v63
	s_nop 0
	v_cvt_pk_bf16_f32 v32, v32, v33
	v_cvt_pk_bf16_f32 v33, v34, v35
	v_cvt_pk_bf16_f32 v34, v36, v37
	v_cvt_pk_bf16_f32 v35, v38, v39
	v_cvt_pk_bf16_f32 v36, v40, v41
	v_cvt_pk_bf16_f32 v37, v42, v43
	v_cvt_pk_bf16_f32 v38, v44, v45
	v_cvt_pk_bf16_f32 v39, v46, v47
	v_cvt_pk_bf16_f32 v48, v48, v49
	v_cvt_pk_bf16_f32 v49, v50, v51
	v_cvt_pk_bf16_f32 v50, v52, v53
	v_cvt_pk_bf16_f32 v51, v54, v55
	v_cvt_pk_bf16_f32 v52, v56, v57
	v_cvt_pk_bf16_f32 v53, v58, v59
	v_cvt_pk_bf16_f32 v54, v60, v61
	v_cvt_pk_bf16_f32 v55, v62, v63
	v_permlane32_swap_b32_e32 v32, v34
	v_permlane32_swap_b32_e32 v33, v35
	v_permlane32_swap_b32_e32 v36, v38
	v_permlane32_swap_b32_e32 v37, v39
	v_permlane32_swap_b32_e32 v48, v50
	v_permlane32_swap_b32_e32 v49, v51
	v_permlane32_swap_b32_e32 v52, v54
	v_permlane32_swap_b32_e32 v53, v55
	s_nop 1
	s_mov_b32 vcc_lo, 0x55555555
	s_mov_b32 vcc_hi, 0x55555555
	v_cndmask_b32_dpp v128, v36, v32, vcc quad_perm:[1,0,3,2] row_mask:0xf bank_mask:0xf
	v_cndmask_b32_dpp v129, v37, v33, vcc quad_perm:[1,0,3,2] row_mask:0xf bank_mask:0xf
	v_cndmask_b32_dpp v130, v38, v34, vcc quad_perm:[1,0,3,2] row_mask:0xf bank_mask:0xf
	v_cndmask_b32_dpp v131, v39, v35, vcc quad_perm:[1,0,3,2] row_mask:0xf bank_mask:0xf
	v_cndmask_b32_dpp v136, v52, v48, vcc quad_perm:[1,0,3,2] row_mask:0xf bank_mask:0xf
	v_cndmask_b32_dpp v137, v53, v49, vcc quad_perm:[1,0,3,2] row_mask:0xf bank_mask:0xf
	v_cndmask_b32_dpp v138, v54, v50, vcc quad_perm:[1,0,3,2] row_mask:0xf bank_mask:0xf
	v_cndmask_b32_dpp v139, v55, v51, vcc quad_perm:[1,0,3,2] row_mask:0xf bank_mask:0xf
	s_mov_b32 vcc_lo, 0xaaaaaaaa
	s_mov_b32 vcc_hi, 0xaaaaaaaa
	v_cndmask_b32_dpp v132, v32, v36, vcc quad_perm:[1,0,3,2] row_mask:0xf bank_mask:0xf
	v_cndmask_b32_dpp v133, v33, v37, vcc quad_perm:[1,0,3,2] row_mask:0xf bank_mask:0xf
	v_cndmask_b32_dpp v134, v34, v38, vcc quad_perm:[1,0,3,2] row_mask:0xf bank_mask:0xf
	v_cndmask_b32_dpp v135, v35, v39, vcc quad_perm:[1,0,3,2] row_mask:0xf bank_mask:0xf
	v_cndmask_b32_dpp v140, v48, v52, vcc quad_perm:[1,0,3,2] row_mask:0xf bank_mask:0xf
	v_cndmask_b32_dpp v141, v49, v53, vcc quad_perm:[1,0,3,2] row_mask:0xf bank_mask:0xf
	v_cndmask_b32_dpp v142, v50, v54, vcc quad_perm:[1,0,3,2] row_mask:0xf bank_mask:0xf
	v_cndmask_b32_dpp v143, v51, v55, vcc quad_perm:[1,0,3,2] row_mask:0xf bank_mask:0xf
	s_nop 1
	s_mov_b32 vcc_lo, 0x33333333
	s_mov_b32 vcc_hi, 0x33333333
	v_cndmask_b32_dpp v32, v136, v128, vcc quad_perm:[2,3,0,1] row_mask:0xf bank_mask:0xf
	v_cndmask_b32_dpp v33, v137, v129, vcc quad_perm:[2,3,0,1] row_mask:0xf bank_mask:0xf
	v_cndmask_b32_dpp v34, v138, v130, vcc quad_perm:[2,3,0,1] row_mask:0xf bank_mask:0xf
	v_cndmask_b32_dpp v35, v139, v131, vcc quad_perm:[2,3,0,1] row_mask:0xf bank_mask:0xf
	v_cndmask_b32_dpp v36, v140, v132, vcc quad_perm:[2,3,0,1] row_mask:0xf bank_mask:0xf
	v_cndmask_b32_dpp v37, v141, v133, vcc quad_perm:[2,3,0,1] row_mask:0xf bank_mask:0xf
	v_cndmask_b32_dpp v38, v142, v134, vcc quad_perm:[2,3,0,1] row_mask:0xf bank_mask:0xf
	v_cndmask_b32_dpp v39, v143, v135, vcc quad_perm:[2,3,0,1] row_mask:0xf bank_mask:0xf
	s_mov_b32 vcc_lo, 0xcccccccc
	s_mov_b32 vcc_hi, 0xcccccccc
	v_cndmask_b32_dpp v48, v128, v136, vcc quad_perm:[2,3,0,1] row_mask:0xf bank_mask:0xf
	v_cndmask_b32_dpp v49, v129, v137, vcc quad_perm:[2,3,0,1] row_mask:0xf bank_mask:0xf
	v_cndmask_b32_dpp v50, v130, v138, vcc quad_perm:[2,3,0,1] row_mask:0xf bank_mask:0xf
	v_cndmask_b32_dpp v51, v131, v139, vcc quad_perm:[2,3,0,1] row_mask:0xf bank_mask:0xf
	v_cndmask_b32_dpp v52, v132, v140, vcc quad_perm:[2,3,0,1] row_mask:0xf bank_mask:0xf
	v_cndmask_b32_dpp v53, v133, v141, vcc quad_perm:[2,3,0,1] row_mask:0xf bank_mask:0xf
	v_cndmask_b32_dpp v54, v134, v142, vcc quad_perm:[2,3,0,1] row_mask:0xf bank_mask:0xf
	v_cndmask_b32_dpp v55, v135, v143, vcc quad_perm:[2,3,0,1] row_mask:0xf bank_mask:0xf
	s_add_u32 s76, s74, 0x0
	s_addc_u32 s77, s75, 0
	global_store_dwordx4 v181, v[32:35], s[76:77]
	s_add_u32 s76, s74, 0x2200
	s_addc_u32 s77, s75, 0
	global_store_dwordx4 v181, v[36:39], s[76:77]
	s_add_u32 s76, s74, 0x4400
	s_addc_u32 s77, s75, 0
	global_store_dwordx4 v181, v[48:51], s[76:77]
	s_add_u32 s76, s74, 0x6600
	s_addc_u32 s77, s75, 0
	global_store_dwordx4 v181, v[52:55], s[76:77]
	s_add_u32 s74, s74, 0x44000
	s_addc_u32 s75, s75, 0
	v_pk_fma_f32 v[64:65], v[64:65], v[174:175], v[198:199] op_sel_hi:[1,0,1]
	v_pk_fma_f32 v[66:67], v[66:67], v[174:175], v[200:201] op_sel_hi:[1,0,1]
	v_pk_fma_f32 v[68:69], v[68:69], v[174:175], v[202:203] op_sel_hi:[1,0,1]
	v_pk_fma_f32 v[70:71], v[70:71], v[174:175], v[204:205] op_sel_hi:[1,0,1]
	v_pk_fma_f32 v[72:73], v[72:73], v[174:175], v[206:207] op_sel_hi:[1,0,1]
	v_pk_fma_f32 v[74:75], v[74:75], v[174:175], v[208:209] op_sel_hi:[1,0,1]
	v_pk_fma_f32 v[76:77], v[76:77], v[174:175], v[210:211] op_sel_hi:[1,0,1]
	v_pk_fma_f32 v[78:79], v[78:79], v[174:175], v[212:213] op_sel_hi:[1,0,1]
	v_pk_fma_f32 v[80:81], v[80:81], v[174:175], v[214:215] op_sel_hi:[1,0,1]
	v_pk_fma_f32 v[82:83], v[82:83], v[174:175], v[216:217] op_sel_hi:[1,0,1]
	v_pk_fma_f32 v[84:85], v[84:85], v[174:175], v[218:219] op_sel_hi:[1,0,1]
	v_pk_fma_f32 v[86:87], v[86:87], v[174:175], v[220:221] op_sel_hi:[1,0,1]
	v_pk_fma_f32 v[88:89], v[88:89], v[174:175], v[222:223] op_sel_hi:[1,0,1]
	v_pk_fma_f32 v[90:91], v[90:91], v[174:175], v[224:225] op_sel_hi:[1,0,1]
	v_pk_fma_f32 v[92:93], v[92:93], v[174:175], v[226:227] op_sel_hi:[1,0,1]
	v_pk_fma_f32 v[94:95], v[94:95], v[174:175], v[228:229] op_sel_hi:[1,0,1]
	v_exp_f32_e32 v64, v64
	v_exp_f32_e32 v65, v65
	v_exp_f32_e32 v66, v66
	v_exp_f32_e32 v67, v67
	v_exp_f32_e32 v68, v68
	v_exp_f32_e32 v69, v69
	v_exp_f32_e32 v70, v70
	v_exp_f32_e32 v71, v71
	v_exp_f32_e32 v72, v72
	v_exp_f32_e32 v73, v73
	v_exp_f32_e32 v74, v74
	v_exp_f32_e32 v75, v75
	v_exp_f32_e32 v76, v76
	v_exp_f32_e32 v77, v77
	v_exp_f32_e32 v78, v78
	v_exp_f32_e32 v79, v79
	v_exp_f32_e32 v80, v80
	v_exp_f32_e32 v81, v81
	v_exp_f32_e32 v82, v82
	v_exp_f32_e32 v83, v83
	v_exp_f32_e32 v84, v84
	v_exp_f32_e32 v85, v85
	v_exp_f32_e32 v86, v86
	v_exp_f32_e32 v87, v87
	v_exp_f32_e32 v88, v88
	v_exp_f32_e32 v89, v89
	v_exp_f32_e32 v90, v90
	v_exp_f32_e32 v91, v91
	v_exp_f32_e32 v92, v92
	v_exp_f32_e32 v93, v93
	v_exp_f32_e32 v94, v94
	v_exp_f32_e32 v95, v95
	v_pk_add_f32 v[64:65], v[64:65], 1.0 op_sel_hi:[1,0]
	v_pk_add_f32 v[66:67], v[66:67], 1.0 op_sel_hi:[1,0]
	v_pk_add_f32 v[68:69], v[68:69], 1.0 op_sel_hi:[1,0]
	v_pk_add_f32 v[70:71], v[70:71], 1.0 op_sel_hi:[1,0]
	v_pk_add_f32 v[72:73], v[72:73], 1.0 op_sel_hi:[1,0]
	v_pk_add_f32 v[74:75], v[74:75], 1.0 op_sel_hi:[1,0]
	v_pk_add_f32 v[76:77], v[76:77], 1.0 op_sel_hi:[1,0]
	v_pk_add_f32 v[78:79], v[78:79], 1.0 op_sel_hi:[1,0]
	v_pk_add_f32 v[80:81], v[80:81], 1.0 op_sel_hi:[1,0]
	v_pk_add_f32 v[82:83], v[82:83], 1.0 op_sel_hi:[1,0]
	v_pk_add_f32 v[84:85], v[84:85], 1.0 op_sel_hi:[1,0]
	v_pk_add_f32 v[86:87], v[86:87], 1.0 op_sel_hi:[1,0]
	v_pk_add_f32 v[88:89], v[88:89], 1.0 op_sel_hi:[1,0]
	v_pk_add_f32 v[90:91], v[90:91], 1.0 op_sel_hi:[1,0]
	v_pk_add_f32 v[92:93], v[92:93], 1.0 op_sel_hi:[1,0]
	v_pk_add_f32 v[94:95], v[94:95], 1.0 op_sel_hi:[1,0]
	v_rcp_f32_e32 v64, v64
	v_rcp_f32_e32 v65, v65
	v_rcp_f32_e32 v66, v66
	v_rcp_f32_e32 v67, v67
	v_rcp_f32_e32 v68, v68
	v_rcp_f32_e32 v69, v69
	v_rcp_f32_e32 v70, v70
	v_rcp_f32_e32 v71, v71
	v_rcp_f32_e32 v72, v72
	v_rcp_f32_e32 v73, v73
	v_rcp_f32_e32 v74, v74
	v_rcp_f32_e32 v75, v75
	v_rcp_f32_e32 v76, v76
	v_rcp_f32_e32 v77, v77
	v_rcp_f32_e32 v78, v78
	v_rcp_f32_e32 v79, v79
	v_rcp_f32_e32 v80, v80
	v_rcp_f32_e32 v81, v81
	v_rcp_f32_e32 v82, v82
	v_rcp_f32_e32 v83, v83
	v_rcp_f32_e32 v84, v84
	v_rcp_f32_e32 v85, v85
	v_rcp_f32_e32 v86, v86
	v_rcp_f32_e32 v87, v87
	v_rcp_f32_e32 v88, v88
	v_rcp_f32_e32 v89, v89
	v_rcp_f32_e32 v90, v90
	v_rcp_f32_e32 v91, v91
	v_rcp_f32_e32 v92, v92
	v_rcp_f32_e32 v93, v93
	v_rcp_f32_e32 v94, v94
	v_rcp_f32_e32 v95, v95
	s_nop 0
	v_cvt_pk_bf16_f32 v64, v64, v65
	v_cvt_pk_bf16_f32 v65, v66, v67
	v_cvt_pk_bf16_f32 v66, v68, v69
	v_cvt_pk_bf16_f32 v67, v70, v71
	v_cvt_pk_bf16_f32 v68, v72, v73
	v_cvt_pk_bf16_f32 v69, v74, v75
	v_cvt_pk_bf16_f32 v70, v76, v77
	v_cvt_pk_bf16_f32 v71, v78, v79
	v_cvt_pk_bf16_f32 v80, v80, v81
	v_cvt_pk_bf16_f32 v81, v82, v83
	v_cvt_pk_bf16_f32 v82, v84, v85
	v_cvt_pk_bf16_f32 v83, v86, v87
	v_cvt_pk_bf16_f32 v84, v88, v89
	v_cvt_pk_bf16_f32 v85, v90, v91
	v_cvt_pk_bf16_f32 v86, v92, v93
	v_cvt_pk_bf16_f32 v87, v94, v95
	v_permlane32_swap_b32_e32 v64, v66
	v_permlane32_swap_b32_e32 v65, v67
	v_permlane32_swap_b32_e32 v68, v70
	v_permlane32_swap_b32_e32 v69, v71
	v_permlane32_swap_b32_e32 v80, v82
	v_permlane32_swap_b32_e32 v81, v83
	v_permlane32_swap_b32_e32 v84, v86
	v_permlane32_swap_b32_e32 v85, v87
	s_nop 1
	s_mov_b32 vcc_lo, 0x55555555
	s_mov_b32 vcc_hi, 0x55555555
	v_cndmask_b32_dpp v128, v68, v64, vcc quad_perm:[1,0,3,2] row_mask:0xf bank_mask:0xf
	v_cndmask_b32_dpp v129, v69, v65, vcc quad_perm:[1,0,3,2] row_mask:0xf bank_mask:0xf
	v_cndmask_b32_dpp v130, v70, v66, vcc quad_perm:[1,0,3,2] row_mask:0xf bank_mask:0xf
	v_cndmask_b32_dpp v131, v71, v67, vcc quad_perm:[1,0,3,2] row_mask:0xf bank_mask:0xf
	v_cndmask_b32_dpp v136, v84, v80, vcc quad_perm:[1,0,3,2] row_mask:0xf bank_mask:0xf
	v_cndmask_b32_dpp v137, v85, v81, vcc quad_perm:[1,0,3,2] row_mask:0xf bank_mask:0xf
	v_cndmask_b32_dpp v138, v86, v82, vcc quad_perm:[1,0,3,2] row_mask:0xf bank_mask:0xf
	v_cndmask_b32_dpp v139, v87, v83, vcc quad_perm:[1,0,3,2] row_mask:0xf bank_mask:0xf
	s_mov_b32 vcc_lo, 0xaaaaaaaa
	s_mov_b32 vcc_hi, 0xaaaaaaaa
	v_cndmask_b32_dpp v132, v64, v68, vcc quad_perm:[1,0,3,2] row_mask:0xf bank_mask:0xf
	v_cndmask_b32_dpp v133, v65, v69, vcc quad_perm:[1,0,3,2] row_mask:0xf bank_mask:0xf
	v_cndmask_b32_dpp v134, v66, v70, vcc quad_perm:[1,0,3,2] row_mask:0xf bank_mask:0xf
	v_cndmask_b32_dpp v135, v67, v71, vcc quad_perm:[1,0,3,2] row_mask:0xf bank_mask:0xf
	v_cndmask_b32_dpp v140, v80, v84, vcc quad_perm:[1,0,3,2] row_mask:0xf bank_mask:0xf
	v_cndmask_b32_dpp v141, v81, v85, vcc quad_perm:[1,0,3,2] row_mask:0xf bank_mask:0xf
	v_cndmask_b32_dpp v142, v82, v86, vcc quad_perm:[1,0,3,2] row_mask:0xf bank_mask:0xf
	v_cndmask_b32_dpp v143, v83, v87, vcc quad_perm:[1,0,3,2] row_mask:0xf bank_mask:0xf
	s_nop 1
	s_mov_b32 vcc_lo, 0x33333333
	s_mov_b32 vcc_hi, 0x33333333
	v_cndmask_b32_dpp v64, v136, v128, vcc quad_perm:[2,3,0,1] row_mask:0xf bank_mask:0xf
	v_cndmask_b32_dpp v65, v137, v129, vcc quad_perm:[2,3,0,1] row_mask:0xf bank_mask:0xf
	v_cndmask_b32_dpp v66, v138, v130, vcc quad_perm:[2,3,0,1] row_mask:0xf bank_mask:0xf
	v_cndmask_b32_dpp v67, v139, v131, vcc quad_perm:[2,3,0,1] row_mask:0xf bank_mask:0xf
	v_cndmask_b32_dpp v68, v140, v132, vcc quad_perm:[2,3,0,1] row_mask:0xf bank_mask:0xf
	v_cndmask_b32_dpp v69, v141, v133, vcc quad_perm:[2,3,0,1] row_mask:0xf bank_mask:0xf
	v_cndmask_b32_dpp v70, v142, v134, vcc quad_perm:[2,3,0,1] row_mask:0xf bank_mask:0xf
	v_cndmask_b32_dpp v71, v143, v135, vcc quad_perm:[2,3,0,1] row_mask:0xf bank_mask:0xf
	s_mov_b32 vcc_lo, 0xcccccccc
	s_mov_b32 vcc_hi, 0xcccccccc
	v_cndmask_b32_dpp v80, v128, v136, vcc quad_perm:[2,3,0,1] row_mask:0xf bank_mask:0xf
	v_cndmask_b32_dpp v81, v129, v137, vcc quad_perm:[2,3,0,1] row_mask:0xf bank_mask:0xf
	v_cndmask_b32_dpp v82, v130, v138, vcc quad_perm:[2,3,0,1] row_mask:0xf bank_mask:0xf
	v_cndmask_b32_dpp v83, v131, v139, vcc quad_perm:[2,3,0,1] row_mask:0xf bank_mask:0xf
	v_cndmask_b32_dpp v84, v132, v140, vcc quad_perm:[2,3,0,1] row_mask:0xf bank_mask:0xf
	v_cndmask_b32_dpp v85, v133, v141, vcc quad_perm:[2,3,0,1] row_mask:0xf bank_mask:0xf
	v_cndmask_b32_dpp v86, v134, v142, vcc quad_perm:[2,3,0,1] row_mask:0xf bank_mask:0xf
	v_cndmask_b32_dpp v87, v135, v143, vcc quad_perm:[2,3,0,1] row_mask:0xf bank_mask:0xf
	s_add_u32 s76, s74, 0x0
	s_addc_u32 s77, s75, 0
	global_store_dwordx4 v181, v[64:67], s[76:77]
	s_add_u32 s76, s74, 0x2200
	s_addc_u32 s77, s75, 0
	global_store_dwordx4 v181, v[68:71], s[76:77]
	s_add_u32 s76, s74, 0x4400
	s_addc_u32 s77, s75, 0
	global_store_dwordx4 v181, v[80:83], s[76:77]
	s_add_u32 s76, s74, 0x6600
	s_addc_u32 s77, s75, 0
	global_store_dwordx4 v181, v[84:87], s[76:77]
	s_add_u32 s74, s74, 0x44000
	s_addc_u32 s75, s75, 0
	v_pk_fma_f32 v[96:97], v[96:97], v[174:175], v[198:199] op_sel:[0,1,0] op_sel_hi:[1,1,1]
	v_pk_fma_f32 v[98:99], v[98:99], v[174:175], v[200:201] op_sel:[0,1,0] op_sel_hi:[1,1,1]
	v_pk_fma_f32 v[100:101], v[100:101], v[174:175], v[202:203] op_sel:[0,1,0] op_sel_hi:[1,1,1]
	v_pk_fma_f32 v[102:103], v[102:103], v[174:175], v[204:205] op_sel:[0,1,0] op_sel_hi:[1,1,1]
	v_pk_fma_f32 v[104:105], v[104:105], v[174:175], v[206:207] op_sel:[0,1,0] op_sel_hi:[1,1,1]
	v_pk_fma_f32 v[106:107], v[106:107], v[174:175], v[208:209] op_sel:[0,1,0] op_sel_hi:[1,1,1]
	v_pk_fma_f32 v[108:109], v[108:109], v[174:175], v[210:211] op_sel:[0,1,0] op_sel_hi:[1,1,1]
	v_pk_fma_f32 v[110:111], v[110:111], v[174:175], v[212:213] op_sel:[0,1,0] op_sel_hi:[1,1,1]
	v_pk_fma_f32 v[112:113], v[112:113], v[174:175], v[214:215] op_sel:[0,1,0] op_sel_hi:[1,1,1]
	v_pk_fma_f32 v[114:115], v[114:115], v[174:175], v[216:217] op_sel:[0,1,0] op_sel_hi:[1,1,1]
	v_pk_fma_f32 v[116:117], v[116:117], v[174:175], v[218:219] op_sel:[0,1,0] op_sel_hi:[1,1,1]
	v_pk_fma_f32 v[118:119], v[118:119], v[174:175], v[220:221] op_sel:[0,1,0] op_sel_hi:[1,1,1]
	v_pk_fma_f32 v[120:121], v[120:121], v[174:175], v[222:223] op_sel:[0,1,0] op_sel_hi:[1,1,1]
	v_pk_fma_f32 v[122:123], v[122:123], v[174:175], v[224:225] op_sel:[0,1,0] op_sel_hi:[1,1,1]
	v_pk_fma_f32 v[124:125], v[124:125], v[174:175], v[226:227] op_sel:[0,1,0] op_sel_hi:[1,1,1]
	v_pk_fma_f32 v[126:127], v[126:127], v[174:175], v[228:229] op_sel:[0,1,0] op_sel_hi:[1,1,1]
	v_exp_f32_e32 v96, v96
	v_exp_f32_e32 v97, v97
	v_exp_f32_e32 v98, v98
	v_exp_f32_e32 v99, v99
	v_exp_f32_e32 v100, v100
	v_exp_f32_e32 v101, v101
	v_exp_f32_e32 v102, v102
	v_exp_f32_e32 v103, v103
	v_exp_f32_e32 v104, v104
	v_exp_f32_e32 v105, v105
	v_exp_f32_e32 v106, v106
	v_exp_f32_e32 v107, v107
	v_exp_f32_e32 v108, v108
	v_exp_f32_e32 v109, v109
	v_exp_f32_e32 v110, v110
	v_exp_f32_e32 v111, v111
	v_exp_f32_e32 v112, v112
	v_exp_f32_e32 v113, v113
	v_exp_f32_e32 v114, v114
	v_exp_f32_e32 v115, v115
	v_exp_f32_e32 v116, v116
	v_exp_f32_e32 v117, v117
	v_exp_f32_e32 v118, v118
	v_exp_f32_e32 v119, v119
	v_exp_f32_e32 v120, v120
	v_exp_f32_e32 v121, v121
	v_exp_f32_e32 v122, v122
	v_exp_f32_e32 v123, v123
	v_exp_f32_e32 v124, v124
	v_exp_f32_e32 v125, v125
	v_exp_f32_e32 v126, v126
	v_exp_f32_e32 v127, v127
	v_pk_add_f32 v[96:97], v[96:97], 1.0 op_sel_hi:[1,0]
	v_pk_add_f32 v[98:99], v[98:99], 1.0 op_sel_hi:[1,0]
	v_pk_add_f32 v[100:101], v[100:101], 1.0 op_sel_hi:[1,0]
	v_pk_add_f32 v[102:103], v[102:103], 1.0 op_sel_hi:[1,0]
	v_pk_add_f32 v[104:105], v[104:105], 1.0 op_sel_hi:[1,0]
	v_pk_add_f32 v[106:107], v[106:107], 1.0 op_sel_hi:[1,0]
	v_pk_add_f32 v[108:109], v[108:109], 1.0 op_sel_hi:[1,0]
	v_pk_add_f32 v[110:111], v[110:111], 1.0 op_sel_hi:[1,0]
	v_pk_add_f32 v[112:113], v[112:113], 1.0 op_sel_hi:[1,0]
	v_pk_add_f32 v[114:115], v[114:115], 1.0 op_sel_hi:[1,0]
	v_pk_add_f32 v[116:117], v[116:117], 1.0 op_sel_hi:[1,0]
	v_pk_add_f32 v[118:119], v[118:119], 1.0 op_sel_hi:[1,0]
	v_pk_add_f32 v[120:121], v[120:121], 1.0 op_sel_hi:[1,0]
	v_pk_add_f32 v[122:123], v[122:123], 1.0 op_sel_hi:[1,0]
	v_pk_add_f32 v[124:125], v[124:125], 1.0 op_sel_hi:[1,0]
	v_pk_add_f32 v[126:127], v[126:127], 1.0 op_sel_hi:[1,0]
	v_rcp_f32_e32 v96, v96
	v_rcp_f32_e32 v97, v97
	v_rcp_f32_e32 v98, v98
	v_rcp_f32_e32 v99, v99
	v_rcp_f32_e32 v100, v100
	v_rcp_f32_e32 v101, v101
	v_rcp_f32_e32 v102, v102
	v_rcp_f32_e32 v103, v103
	v_rcp_f32_e32 v104, v104
	v_rcp_f32_e32 v105, v105
	v_rcp_f32_e32 v106, v106
	v_rcp_f32_e32 v107, v107
	v_rcp_f32_e32 v108, v108
	v_rcp_f32_e32 v109, v109
	v_rcp_f32_e32 v110, v110
	v_rcp_f32_e32 v111, v111
	v_rcp_f32_e32 v112, v112
	v_rcp_f32_e32 v113, v113
	v_rcp_f32_e32 v114, v114
	v_rcp_f32_e32 v115, v115
	v_rcp_f32_e32 v116, v116
	v_rcp_f32_e32 v117, v117
	v_rcp_f32_e32 v118, v118
	v_rcp_f32_e32 v119, v119
	v_rcp_f32_e32 v120, v120
	v_rcp_f32_e32 v121, v121
	v_rcp_f32_e32 v122, v122
	v_rcp_f32_e32 v123, v123
	v_rcp_f32_e32 v124, v124
	v_rcp_f32_e32 v125, v125
	v_rcp_f32_e32 v126, v126
	v_rcp_f32_e32 v127, v127
	s_nop 0
	v_cvt_pk_bf16_f32 v96, v96, v97
	v_cvt_pk_bf16_f32 v97, v98, v99
	v_cvt_pk_bf16_f32 v98, v100, v101
	v_cvt_pk_bf16_f32 v99, v102, v103
	v_cvt_pk_bf16_f32 v100, v104, v105
	v_cvt_pk_bf16_f32 v101, v106, v107
	v_cvt_pk_bf16_f32 v102, v108, v109
	v_cvt_pk_bf16_f32 v103, v110, v111
	v_cvt_pk_bf16_f32 v112, v112, v113
	v_cvt_pk_bf16_f32 v113, v114, v115
	v_cvt_pk_bf16_f32 v114, v116, v117
	v_cvt_pk_bf16_f32 v115, v118, v119
	v_cvt_pk_bf16_f32 v116, v120, v121
	v_cvt_pk_bf16_f32 v117, v122, v123
	v_cvt_pk_bf16_f32 v118, v124, v125
	v_cvt_pk_bf16_f32 v119, v126, v127
	v_permlane32_swap_b32_e32 v96, v98
	v_permlane32_swap_b32_e32 v97, v99
	v_permlane32_swap_b32_e32 v100, v102
	v_permlane32_swap_b32_e32 v101, v103
	v_permlane32_swap_b32_e32 v112, v114
	v_permlane32_swap_b32_e32 v113, v115
	v_permlane32_swap_b32_e32 v116, v118
	v_permlane32_swap_b32_e32 v117, v119
	s_nop 1
	s_mov_b32 vcc_lo, 0x55555555
	s_mov_b32 vcc_hi, 0x55555555
	v_cndmask_b32_dpp v128, v100, v96, vcc quad_perm:[1,0,3,2] row_mask:0xf bank_mask:0xf
	v_cndmask_b32_dpp v129, v101, v97, vcc quad_perm:[1,0,3,2] row_mask:0xf bank_mask:0xf
	v_cndmask_b32_dpp v130, v102, v98, vcc quad_perm:[1,0,3,2] row_mask:0xf bank_mask:0xf
	v_cndmask_b32_dpp v131, v103, v99, vcc quad_perm:[1,0,3,2] row_mask:0xf bank_mask:0xf
	v_cndmask_b32_dpp v136, v116, v112, vcc quad_perm:[1,0,3,2] row_mask:0xf bank_mask:0xf
	v_cndmask_b32_dpp v137, v117, v113, vcc quad_perm:[1,0,3,2] row_mask:0xf bank_mask:0xf
	v_cndmask_b32_dpp v138, v118, v114, vcc quad_perm:[1,0,3,2] row_mask:0xf bank_mask:0xf
	v_cndmask_b32_dpp v139, v119, v115, vcc quad_perm:[1,0,3,2] row_mask:0xf bank_mask:0xf
	s_mov_b32 vcc_lo, 0xaaaaaaaa
	s_mov_b32 vcc_hi, 0xaaaaaaaa
	v_cndmask_b32_dpp v132, v96, v100, vcc quad_perm:[1,0,3,2] row_mask:0xf bank_mask:0xf
	v_cndmask_b32_dpp v133, v97, v101, vcc quad_perm:[1,0,3,2] row_mask:0xf bank_mask:0xf
	v_cndmask_b32_dpp v134, v98, v102, vcc quad_perm:[1,0,3,2] row_mask:0xf bank_mask:0xf
	v_cndmask_b32_dpp v135, v99, v103, vcc quad_perm:[1,0,3,2] row_mask:0xf bank_mask:0xf
	v_cndmask_b32_dpp v140, v112, v116, vcc quad_perm:[1,0,3,2] row_mask:0xf bank_mask:0xf
	v_cndmask_b32_dpp v141, v113, v117, vcc quad_perm:[1,0,3,2] row_mask:0xf bank_mask:0xf
	v_cndmask_b32_dpp v142, v114, v118, vcc quad_perm:[1,0,3,2] row_mask:0xf bank_mask:0xf
	v_cndmask_b32_dpp v143, v115, v119, vcc quad_perm:[1,0,3,2] row_mask:0xf bank_mask:0xf
	s_nop 1
	s_mov_b32 vcc_lo, 0x33333333
	s_mov_b32 vcc_hi, 0x33333333
	v_cndmask_b32_dpp v96, v136, v128, vcc quad_perm:[2,3,0,1] row_mask:0xf bank_mask:0xf
	v_cndmask_b32_dpp v97, v137, v129, vcc quad_perm:[2,3,0,1] row_mask:0xf bank_mask:0xf
	v_cndmask_b32_dpp v98, v138, v130, vcc quad_perm:[2,3,0,1] row_mask:0xf bank_mask:0xf
	v_cndmask_b32_dpp v99, v139, v131, vcc quad_perm:[2,3,0,1] row_mask:0xf bank_mask:0xf
	v_cndmask_b32_dpp v100, v140, v132, vcc quad_perm:[2,3,0,1] row_mask:0xf bank_mask:0xf
	v_cndmask_b32_dpp v101, v141, v133, vcc quad_perm:[2,3,0,1] row_mask:0xf bank_mask:0xf
	v_cndmask_b32_dpp v102, v142, v134, vcc quad_perm:[2,3,0,1] row_mask:0xf bank_mask:0xf
	v_cndmask_b32_dpp v103, v143, v135, vcc quad_perm:[2,3,0,1] row_mask:0xf bank_mask:0xf
	s_mov_b32 vcc_lo, 0xcccccccc
	s_mov_b32 vcc_hi, 0xcccccccc
	v_cndmask_b32_dpp v112, v128, v136, vcc quad_perm:[2,3,0,1] row_mask:0xf bank_mask:0xf
	v_cndmask_b32_dpp v113, v129, v137, vcc quad_perm:[2,3,0,1] row_mask:0xf bank_mask:0xf
	v_cndmask_b32_dpp v114, v130, v138, vcc quad_perm:[2,3,0,1] row_mask:0xf bank_mask:0xf
	v_cndmask_b32_dpp v115, v131, v139, vcc quad_perm:[2,3,0,1] row_mask:0xf bank_mask:0xf
	v_cndmask_b32_dpp v116, v132, v140, vcc quad_perm:[2,3,0,1] row_mask:0xf bank_mask:0xf
	v_cndmask_b32_dpp v117, v133, v141, vcc quad_perm:[2,3,0,1] row_mask:0xf bank_mask:0xf
	v_cndmask_b32_dpp v118, v134, v142, vcc quad_perm:[2,3,0,1] row_mask:0xf bank_mask:0xf
	v_cndmask_b32_dpp v119, v135, v143, vcc quad_perm:[2,3,0,1] row_mask:0xf bank_mask:0xf
	s_add_u32 s76, s74, 0x0
	s_addc_u32 s77, s75, 0
	global_store_dwordx4 v181, v[96:99], s[76:77]
	s_add_u32 s76, s74, 0x2200
	s_addc_u32 s77, s75, 0
	global_store_dwordx4 v181, v[100:103], s[76:77]
	s_add_u32 s76, s74, 0x4400
	s_addc_u32 s77, s75, 0
	global_store_dwordx4 v181, v[112:115], s[76:77]
	s_add_u32 s76, s74, 0x6600
	s_addc_u32 s77, s75, 0
	global_store_dwordx4 v181, v[116:119], s[76:77]
	s_branch .Lpe_ret_L0

.Lpe_gates_L1:
	s_lshl_b32 s35, s98, 11
	s_add_u32 s35, s35, s30
	s_sub_u32 s35, s35, 0x900
	s_lshl_b32 s35, s35, 2
	v_readlane_b32 s82, v254, 12
	v_readlane_b32 s83, v254, 13
	s_add_u32 s82, s82, s35
	s_addc_u32 s83, s83, 0
	global_load_dwordx4 v[198:201], v146, s[82:83] offset:0
	global_load_dwordx4 v[202:205], v146, s[82:83] offset:32
	global_load_dwordx4 v[206:209], v146, s[82:83] offset:64
	global_load_dwordx4 v[210:213], v146, s[82:83] offset:96
	global_load_dwordx4 v[214:217], v146, s[82:83] offset:128
	global_load_dwordx4 v[218:221], v146, s[82:83] offset:160
	global_load_dwordx4 v[222:225], v146, s[82:83] offset:192
	global_load_dwordx4 v[226:229], v146, s[82:83] offset:224
	s_waitcnt vmcnt(8)
	v_mov_b32_e32 v197, 0x358637bd
	v_pk_add_f32 v[128:129], v[128:129], v[130:131]
	v_pk_add_f32 v[132:133], v[132:133], v[134:135]
	v_pk_add_f32 v[136:137], v[136:137], v[138:139]
	v_pk_add_f32 v[140:141], v[140:141], v[142:143]
	v_pk_add_f32 v[164:165], v[164:165], v[166:167]
	v_pk_add_f32 v[168:169], v[168:169], v[170:171]
	v_pk_add_f32 v[246:247], v[246:247], v[248:249]
	v_pk_add_f32 v[250:251], v[250:251], v[252:253]
	v_pk_add_f32 v[128:129], v[128:129], v[132:133]
	v_pk_add_f32 v[136:137], v[136:137], v[140:141]
	v_pk_add_f32 v[164:165], v[164:165], v[168:169]
	v_pk_add_f32 v[246:247], v[246:247], v[250:251]
	v_add_f32_e32 v128, v128, v129
	v_add_f32_e32 v136, v136, v137
	v_add_f32_e32 v164, v164, v165
	v_add_f32_e32 v246, v246, v247
	v_fmamk_f32 v128, v128, 0x3a800000, v197
	v_fmamk_f32 v136, v136, 0x3a800000, v197
	v_fmamk_f32 v164, v164, 0x3a800000, v197
	v_fmamk_f32 v246, v246, 0x3a800000, v197
	v_rsq_f32_e32 v172, v128
	v_rsq_f32_e32 v173, v136
	v_rsq_f32_e32 v174, v164
	v_rsq_f32_e32 v175, v246
	s_nop 0
	s_add_u32 s76, s99, s90
	s_cmp_lt_u32 s76, 0x440
	s_cselect_b32 s80, 1, 0
	s_cselect_b32 s83, 0x200000, 0
	s_lshl_b32 s76, s24, 19
	s_lshl_b32 s77, s26, 16
	s_add_u32 s76, s76, s77
	s_and_b32 s77, s24, 7
	s_lshl_b32 s77, s77, 8
	s_add_u32 s76, s76, s77
	s_add_u32 s78, s72, 0xa120000
	s_addc_u32 s79, s73, 0
	s_add_u32 s78, s78, s76
	s_addc_u32 s79, s79, 0
	s_lshl_b32 s76, s25, 19
	s_add_u32 s76, s76, s83
	s_add_u32 s76, s76, s77
	s_lshl_b32 s77, s26, 16
	s_add_u32 s76, s76, s77
	s_add_u32 s82, s72, 0x880000
	s_addc_u32 s83, s73, 0
	s_add_u32 s82, s82, s76
	s_addc_u32 s83, s83, 0
	s_lshl_b32 s76, s26, 12
	s_mov_b32 m0, s76
	s_nop 0
	global_load_lds_dwordx4 v177, s[78:79]
	s_add_u32 s78, s78, 0x4000
	s_addc_u32 s79, s79, 0
	s_add_u32 s76, s76, 0x400
	s_mov_b32 m0, s76
	s_nop 0
	global_load_lds_dwordx4 v185, s[78:79]
	s_add_u32 s78, s78, 0x4000
	s_addc_u32 s79, s79, 0
	s_add_u32 s76, s76, 0x400
	s_mov_b32 m0, s76
	s_nop 0
	global_load_lds_dwordx4 v177, s[78:79]
	s_add_u32 s78, s78, 0x4000
	s_addc_u32 s79, s79, 0
	s_add_u32 s76, s76, 0x400
	s_mov_b32 m0, s76
	s_nop 0
	global_load_lds_dwordx4 v185, s[78:79]
	s_add_u32 s78, s78, 0x4000
	s_addc_u32 s79, s79, 0
	s_add_u32 s76, s76, 0x400
	s_add_u32 s76, s76, 0x7000
	s_mov_b32 m0, s76
	s_nop 0
	global_load_lds_dwordx4 v177, s[82:83]
	s_add_u32 s82, s82, 0x4000
	s_addc_u32 s83, s83, 0
	s_add_u32 s76, s76, 0x400
	s_mov_b32 m0, s76
	s_nop 0
	global_load_lds_dwordx4 v185, s[82:83]
	s_add_u32 s82, s82, 0x4000
	s_addc_u32 s83, s83, 0
	s_add_u32 s76, s76, 0x400
	s_mov_b32 m0, s76
	s_nop 0
	global_load_lds_dwordx4 v177, s[82:83]
	s_add_u32 s82, s82, 0x4000
	s_addc_u32 s83, s83, 0
	s_add_u32 s76, s76, 0x400
	s_mov_b32 m0, s76
	s_nop 0
	global_load_lds_dwordx4 v185, s[82:83]
	s_add_u32 s82, s82, 0x4000
	s_addc_u32 s83, s83, 0
	s_add_u32 s76, s76, 0x400
	v_mul_f32_e32 v172, 0xbfb8aa3b, v172
	v_mul_f32_e32 v173, 0xbfb8aa3b, v173
	v_mul_f32_e32 v174, 0xbfb8aa3b, v174
	v_mul_f32_e32 v175, 0xbfb8aa3b, v175
	s_waitcnt vmcnt(8)
	v_mul_f32_e32 v198, 0xbfb8aa3b, v198
	v_mul_f32_e32 v199, 0xbfb8aa3b, v199
	v_mul_f32_e32 v200, 0xbfb8aa3b, v200
	v_mul_f32_e32 v201, 0xbfb8aa3b, v201
	v_mul_f32_e32 v202, 0xbfb8aa3b, v202
	v_mul_f32_e32 v203, 0xbfb8aa3b, v203
	v_mul_f32_e32 v204, 0xbfb8aa3b, v204
	v_mul_f32_e32 v205, 0xbfb8aa3b, v205
	v_mul_f32_e32 v206, 0xbfb8aa3b, v206
	v_mul_f32_e32 v207, 0xbfb8aa3b, v207
	v_mul_f32_e32 v208, 0xbfb8aa3b, v208
	v_mul_f32_e32 v209, 0xbfb8aa3b, v209
	v_mul_f32_e32 v210, 0xbfb8aa3b, v210
	v_mul_f32_e32 v211, 0xbfb8aa3b, v211
	v_mul_f32_e32 v212, 0xbfb8aa3b, v212
	v_mul_f32_e32 v213, 0xbfb8aa3b, v213
	v_mul_f32_e32 v214, 0xbfb8aa3b, v214
	v_mul_f32_e32 v215, 0xbfb8aa3b, v215
	v_mul_f32_e32 v216, 0xbfb8aa3b, v216
	v_mul_f32_e32 v217, 0xbfb8aa3b, v217
	v_mul_f32_e32 v218, 0xbfb8aa3b, v218
	v_mul_f32_e32 v219, 0xbfb8aa3b, v219
	v_mul_f32_e32 v220, 0xbfb8aa3b, v220
	v_mul_f32_e32 v221, 0xbfb8aa3b, v221
	v_mul_f32_e32 v222, 0xbfb8aa3b, v222
	v_mul_f32_e32 v223, 0xbfb8aa3b, v223
	v_mul_f32_e32 v224, 0xbfb8aa3b, v224
	v_mul_f32_e32 v225, 0xbfb8aa3b, v225
	v_mul_f32_e32 v226, 0xbfb8aa3b, v226
	v_mul_f32_e32 v227, 0xbfb8aa3b, v227
	v_mul_f32_e32 v228, 0xbfb8aa3b, v228
	v_mul_f32_e32 v229, 0xbfb8aa3b, v229
	v_pk_fma_f32 v[0:1], v[0:1], v[172:173], v[198:199] op_sel_hi:[1,0,1]
	v_pk_fma_f32 v[2:3], v[2:3], v[172:173], v[200:201] op_sel_hi:[1,0,1]
	v_pk_fma_f32 v[4:5], v[4:5], v[172:173], v[202:203] op_sel_hi:[1,0,1]
	v_pk_fma_f32 v[6:7], v[6:7], v[172:173], v[204:205] op_sel_hi:[1,0,1]
	v_pk_fma_f32 v[8:9], v[8:9], v[172:173], v[206:207] op_sel_hi:[1,0,1]
	v_pk_fma_f32 v[10:11], v[10:11], v[172:173], v[208:209] op_sel_hi:[1,0,1]
	v_pk_fma_f32 v[12:13], v[12:13], v[172:173], v[210:211] op_sel_hi:[1,0,1]
	v_pk_fma_f32 v[14:15], v[14:15], v[172:173], v[212:213] op_sel_hi:[1,0,1]
	v_pk_fma_f32 v[16:17], v[16:17], v[172:173], v[214:215] op_sel_hi:[1,0,1]
	v_pk_fma_f32 v[18:19], v[18:19], v[172:173], v[216:217] op_sel_hi:[1,0,1]
	v_pk_fma_f32 v[20:21], v[20:21], v[172:173], v[218:219] op_sel_hi:[1,0,1]
	v_pk_fma_f32 v[22:23], v[22:23], v[172:173], v[220:221] op_sel_hi:[1,0,1]
	v_pk_fma_f32 v[24:25], v[24:25], v[172:173], v[222:223] op_sel_hi:[1,0,1]
	v_pk_fma_f32 v[26:27], v[26:27], v[172:173], v[224:225] op_sel_hi:[1,0,1]
	v_pk_fma_f32 v[28:29], v[28:29], v[172:173], v[226:227] op_sel_hi:[1,0,1]
	v_pk_fma_f32 v[30:31], v[30:31], v[172:173], v[228:229] op_sel_hi:[1,0,1]
	v_exp_f32_e32 v0, v0
	v_exp_f32_e32 v1, v1
	v_exp_f32_e32 v2, v2
	v_exp_f32_e32 v3, v3
	v_exp_f32_e32 v4, v4
	v_exp_f32_e32 v5, v5
	v_exp_f32_e32 v6, v6
	v_exp_f32_e32 v7, v7
	v_exp_f32_e32 v8, v8
	v_exp_f32_e32 v9, v9
	v_exp_f32_e32 v10, v10
	v_exp_f32_e32 v11, v11
	v_exp_f32_e32 v12, v12
	v_exp_f32_e32 v13, v13
	v_exp_f32_e32 v14, v14
	v_exp_f32_e32 v15, v15
	v_exp_f32_e32 v16, v16
	v_exp_f32_e32 v17, v17
	v_exp_f32_e32 v18, v18
	v_exp_f32_e32 v19, v19
	v_exp_f32_e32 v20, v20
	v_exp_f32_e32 v21, v21
	v_exp_f32_e32 v22, v22
	v_exp_f32_e32 v23, v23
	v_exp_f32_e32 v24, v24
	v_exp_f32_e32 v25, v25
	v_exp_f32_e32 v26, v26
	v_exp_f32_e32 v27, v27
	v_exp_f32_e32 v28, v28
	v_exp_f32_e32 v29, v29
	v_exp_f32_e32 v30, v30
	v_exp_f32_e32 v31, v31
	v_pk_add_f32 v[0:1], v[0:1], 1.0 op_sel_hi:[1,0]
	v_pk_add_f32 v[2:3], v[2:3], 1.0 op_sel_hi:[1,0]
	v_pk_add_f32 v[4:5], v[4:5], 1.0 op_sel_hi:[1,0]
	v_pk_add_f32 v[6:7], v[6:7], 1.0 op_sel_hi:[1,0]
	v_pk_add_f32 v[8:9], v[8:9], 1.0 op_sel_hi:[1,0]
	v_pk_add_f32 v[10:11], v[10:11], 1.0 op_sel_hi:[1,0]
	v_pk_add_f32 v[12:13], v[12:13], 1.0 op_sel_hi:[1,0]
	v_pk_add_f32 v[14:15], v[14:15], 1.0 op_sel_hi:[1,0]
	v_pk_add_f32 v[16:17], v[16:17], 1.0 op_sel_hi:[1,0]
	v_pk_add_f32 v[18:19], v[18:19], 1.0 op_sel_hi:[1,0]
	v_pk_add_f32 v[20:21], v[20:21], 1.0 op_sel_hi:[1,0]
	v_pk_add_f32 v[22:23], v[22:23], 1.0 op_sel_hi:[1,0]
	v_pk_add_f32 v[24:25], v[24:25], 1.0 op_sel_hi:[1,0]
	v_pk_add_f32 v[26:27], v[26:27], 1.0 op_sel_hi:[1,0]
	v_pk_add_f32 v[28:29], v[28:29], 1.0 op_sel_hi:[1,0]
	v_pk_add_f32 v[30:31], v[30:31], 1.0 op_sel_hi:[1,0]
	v_rcp_f32_e32 v0, v0
	v_rcp_f32_e32 v1, v1
	v_rcp_f32_e32 v2, v2
	v_rcp_f32_e32 v3, v3
	v_rcp_f32_e32 v4, v4
	v_rcp_f32_e32 v5, v5
	v_rcp_f32_e32 v6, v6
	v_rcp_f32_e32 v7, v7
	v_rcp_f32_e32 v8, v8
	v_rcp_f32_e32 v9, v9
	v_rcp_f32_e32 v10, v10
	v_rcp_f32_e32 v11, v11
	v_rcp_f32_e32 v12, v12
	v_rcp_f32_e32 v13, v13
	v_rcp_f32_e32 v14, v14
	v_rcp_f32_e32 v15, v15
	v_rcp_f32_e32 v16, v16
	v_rcp_f32_e32 v17, v17
	v_rcp_f32_e32 v18, v18
	v_rcp_f32_e32 v19, v19
	v_rcp_f32_e32 v20, v20
	v_rcp_f32_e32 v21, v21
	v_rcp_f32_e32 v22, v22
	v_rcp_f32_e32 v23, v23
	v_rcp_f32_e32 v24, v24
	v_rcp_f32_e32 v25, v25
	v_rcp_f32_e32 v26, v26
	v_rcp_f32_e32 v27, v27
	v_rcp_f32_e32 v28, v28
	v_rcp_f32_e32 v29, v29
	v_rcp_f32_e32 v30, v30
	v_rcp_f32_e32 v31, v31
	s_nop 0
	v_cvt_pk_bf16_f32 v0, v0, v1
	v_cvt_pk_bf16_f32 v1, v2, v3
	v_cvt_pk_bf16_f32 v2, v4, v5
	v_cvt_pk_bf16_f32 v3, v6, v7
	v_cvt_pk_bf16_f32 v4, v8, v9
	v_cvt_pk_bf16_f32 v5, v10, v11
	v_cvt_pk_bf16_f32 v6, v12, v13
	v_cvt_pk_bf16_f32 v7, v14, v15
	v_cvt_pk_bf16_f32 v16, v16, v17
	v_cvt_pk_bf16_f32 v17, v18, v19
	v_cvt_pk_bf16_f32 v18, v20, v21
	v_cvt_pk_bf16_f32 v19, v22, v23
	v_cvt_pk_bf16_f32 v20, v24, v25
	v_cvt_pk_bf16_f32 v21, v26, v27
	v_cvt_pk_bf16_f32 v22, v28, v29
	v_cvt_pk_bf16_f32 v23, v30, v31
	v_permlane32_swap_b32_e32 v0, v2
	v_permlane32_swap_b32_e32 v1, v3
	v_permlane32_swap_b32_e32 v4, v6
	v_permlane32_swap_b32_e32 v5, v7
	v_permlane32_swap_b32_e32 v16, v18
	v_permlane32_swap_b32_e32 v17, v19
	v_permlane32_swap_b32_e32 v20, v22
	v_permlane32_swap_b32_e32 v21, v23
	s_nop 1
	s_mov_b32 vcc_lo, 0x55555555
	s_mov_b32 vcc_hi, 0x55555555
	v_cndmask_b32_dpp v128, v4, v0, vcc quad_perm:[1,0,3,2] row_mask:0xf bank_mask:0xf
	v_cndmask_b32_dpp v129, v5, v1, vcc quad_perm:[1,0,3,2] row_mask:0xf bank_mask:0xf
	v_cndmask_b32_dpp v130, v6, v2, vcc quad_perm:[1,0,3,2] row_mask:0xf bank_mask:0xf
	v_cndmask_b32_dpp v131, v7, v3, vcc quad_perm:[1,0,3,2] row_mask:0xf bank_mask:0xf
	v_cndmask_b32_dpp v136, v20, v16, vcc quad_perm:[1,0,3,2] row_mask:0xf bank_mask:0xf
	v_cndmask_b32_dpp v137, v21, v17, vcc quad_perm:[1,0,3,2] row_mask:0xf bank_mask:0xf
	v_cndmask_b32_dpp v138, v22, v18, vcc quad_perm:[1,0,3,2] row_mask:0xf bank_mask:0xf
	v_cndmask_b32_dpp v139, v23, v19, vcc quad_perm:[1,0,3,2] row_mask:0xf bank_mask:0xf
	s_mov_b32 vcc_lo, 0xaaaaaaaa
	s_mov_b32 vcc_hi, 0xaaaaaaaa
	v_cndmask_b32_dpp v132, v0, v4, vcc quad_perm:[1,0,3,2] row_mask:0xf bank_mask:0xf
	v_cndmask_b32_dpp v133, v1, v5, vcc quad_perm:[1,0,3,2] row_mask:0xf bank_mask:0xf
	v_cndmask_b32_dpp v134, v2, v6, vcc quad_perm:[1,0,3,2] row_mask:0xf bank_mask:0xf
	v_cndmask_b32_dpp v135, v3, v7, vcc quad_perm:[1,0,3,2] row_mask:0xf bank_mask:0xf
	v_cndmask_b32_dpp v140, v16, v20, vcc quad_perm:[1,0,3,2] row_mask:0xf bank_mask:0xf
	v_cndmask_b32_dpp v141, v17, v21, vcc quad_perm:[1,0,3,2] row_mask:0xf bank_mask:0xf
	v_cndmask_b32_dpp v142, v18, v22, vcc quad_perm:[1,0,3,2] row_mask:0xf bank_mask:0xf
	v_cndmask_b32_dpp v143, v19, v23, vcc quad_perm:[1,0,3,2] row_mask:0xf bank_mask:0xf
	s_nop 1
	s_mov_b32 vcc_lo, 0x33333333
	s_mov_b32 vcc_hi, 0x33333333
	v_cndmask_b32_dpp v0, v136, v128, vcc quad_perm:[2,3,0,1] row_mask:0xf bank_mask:0xf
	v_cndmask_b32_dpp v1, v137, v129, vcc quad_perm:[2,3,0,1] row_mask:0xf bank_mask:0xf
	v_cndmask_b32_dpp v2, v138, v130, vcc quad_perm:[2,3,0,1] row_mask:0xf bank_mask:0xf
	v_cndmask_b32_dpp v3, v139, v131, vcc quad_perm:[2,3,0,1] row_mask:0xf bank_mask:0xf
	v_cndmask_b32_dpp v4, v140, v132, vcc quad_perm:[2,3,0,1] row_mask:0xf bank_mask:0xf
	v_cndmask_b32_dpp v5, v141, v133, vcc quad_perm:[2,3,0,1] row_mask:0xf bank_mask:0xf
	v_cndmask_b32_dpp v6, v142, v134, vcc quad_perm:[2,3,0,1] row_mask:0xf bank_mask:0xf
	v_cndmask_b32_dpp v7, v143, v135, vcc quad_perm:[2,3,0,1] row_mask:0xf bank_mask:0xf
	s_mov_b32 vcc_lo, 0xcccccccc
	s_mov_b32 vcc_hi, 0xcccccccc
	v_cndmask_b32_dpp v16, v128, v136, vcc quad_perm:[2,3,0,1] row_mask:0xf bank_mask:0xf
	v_cndmask_b32_dpp v17, v129, v137, vcc quad_perm:[2,3,0,1] row_mask:0xf bank_mask:0xf
	v_cndmask_b32_dpp v18, v130, v138, vcc quad_perm:[2,3,0,1] row_mask:0xf bank_mask:0xf
	v_cndmask_b32_dpp v19, v131, v139, vcc quad_perm:[2,3,0,1] row_mask:0xf bank_mask:0xf
	v_cndmask_b32_dpp v20, v132, v140, vcc quad_perm:[2,3,0,1] row_mask:0xf bank_mask:0xf
	v_cndmask_b32_dpp v21, v133, v141, vcc quad_perm:[2,3,0,1] row_mask:0xf bank_mask:0xf
	v_cndmask_b32_dpp v22, v134, v142, vcc quad_perm:[2,3,0,1] row_mask:0xf bank_mask:0xf
	v_cndmask_b32_dpp v23, v135, v143, vcc quad_perm:[2,3,0,1] row_mask:0xf bank_mask:0xf
	s_add_u32 s76, s74, 0x0
	s_addc_u32 s77, s75, 0
	global_store_dwordx4 v181, v[0:3], s[76:77]
	s_add_u32 s76, s74, 0x2200
	s_addc_u32 s77, s75, 0
	global_store_dwordx4 v181, v[4:7], s[76:77]
	s_add_u32 s76, s74, 0x4400
	s_addc_u32 s77, s75, 0
	global_store_dwordx4 v181, v[16:19], s[76:77]
	s_add_u32 s76, s74, 0x6600
	s_addc_u32 s77, s75, 0
	global_store_dwordx4 v181, v[20:23], s[76:77]
	s_add_u32 s74, s74, 0x44000
	s_addc_u32 s75, s75, 0
	v_pk_fma_f32 v[32:33], v[32:33], v[172:173], v[198:199] op_sel:[0,1,0] op_sel_hi:[1,1,1]
	v_pk_fma_f32 v[34:35], v[34:35], v[172:173], v[200:201] op_sel:[0,1,0] op_sel_hi:[1,1,1]
	v_pk_fma_f32 v[36:37], v[36:37], v[172:173], v[202:203] op_sel:[0,1,0] op_sel_hi:[1,1,1]
	v_pk_fma_f32 v[38:39], v[38:39], v[172:173], v[204:205] op_sel:[0,1,0] op_sel_hi:[1,1,1]
	v_pk_fma_f32 v[40:41], v[40:41], v[172:173], v[206:207] op_sel:[0,1,0] op_sel_hi:[1,1,1]
	v_pk_fma_f32 v[42:43], v[42:43], v[172:173], v[208:209] op_sel:[0,1,0] op_sel_hi:[1,1,1]
	v_pk_fma_f32 v[44:45], v[44:45], v[172:173], v[210:211] op_sel:[0,1,0] op_sel_hi:[1,1,1]
	v_pk_fma_f32 v[46:47], v[46:47], v[172:173], v[212:213] op_sel:[0,1,0] op_sel_hi:[1,1,1]
	v_pk_fma_f32 v[48:49], v[48:49], v[172:173], v[214:215] op_sel:[0,1,0] op_sel_hi:[1,1,1]
	v_pk_fma_f32 v[50:51], v[50:51], v[172:173], v[216:217] op_sel:[0,1,0] op_sel_hi:[1,1,1]
	v_pk_fma_f32 v[52:53], v[52:53], v[172:173], v[218:219] op_sel:[0,1,0] op_sel_hi:[1,1,1]
	v_pk_fma_f32 v[54:55], v[54:55], v[172:173], v[220:221] op_sel:[0,1,0] op_sel_hi:[1,1,1]
	v_pk_fma_f32 v[56:57], v[56:57], v[172:173], v[222:223] op_sel:[0,1,0] op_sel_hi:[1,1,1]
	v_pk_fma_f32 v[58:59], v[58:59], v[172:173], v[224:225] op_sel:[0,1,0] op_sel_hi:[1,1,1]
	v_pk_fma_f32 v[60:61], v[60:61], v[172:173], v[226:227] op_sel:[0,1,0] op_sel_hi:[1,1,1]
	v_pk_fma_f32 v[62:63], v[62:63], v[172:173], v[228:229] op_sel:[0,1,0] op_sel_hi:[1,1,1]
	v_exp_f32_e32 v32, v32
	v_exp_f32_e32 v33, v33
	v_exp_f32_e32 v34, v34
	v_exp_f32_e32 v35, v35
	v_exp_f32_e32 v36, v36
	v_exp_f32_e32 v37, v37
	v_exp_f32_e32 v38, v38
	v_exp_f32_e32 v39, v39
	v_exp_f32_e32 v40, v40
	v_exp_f32_e32 v41, v41
	v_exp_f32_e32 v42, v42
	v_exp_f32_e32 v43, v43
	v_exp_f32_e32 v44, v44
	v_exp_f32_e32 v45, v45
	v_exp_f32_e32 v46, v46
	v_exp_f32_e32 v47, v47
	v_exp_f32_e32 v48, v48
	v_exp_f32_e32 v49, v49
	v_exp_f32_e32 v50, v50
	v_exp_f32_e32 v51, v51
	v_exp_f32_e32 v52, v52
	v_exp_f32_e32 v53, v53
	v_exp_f32_e32 v54, v54
	v_exp_f32_e32 v55, v55
	v_exp_f32_e32 v56, v56
	v_exp_f32_e32 v57, v57
	v_exp_f32_e32 v58, v58
	v_exp_f32_e32 v59, v59
	v_exp_f32_e32 v60, v60
	v_exp_f32_e32 v61, v61
	v_exp_f32_e32 v62, v62
	v_exp_f32_e32 v63, v63
	v_pk_add_f32 v[32:33], v[32:33], 1.0 op_sel_hi:[1,0]
	v_pk_add_f32 v[34:35], v[34:35], 1.0 op_sel_hi:[1,0]
	v_pk_add_f32 v[36:37], v[36:37], 1.0 op_sel_hi:[1,0]
	v_pk_add_f32 v[38:39], v[38:39], 1.0 op_sel_hi:[1,0]
	v_pk_add_f32 v[40:41], v[40:41], 1.0 op_sel_hi:[1,0]
	v_pk_add_f32 v[42:43], v[42:43], 1.0 op_sel_hi:[1,0]
	v_pk_add_f32 v[44:45], v[44:45], 1.0 op_sel_hi:[1,0]
	v_pk_add_f32 v[46:47], v[46:47], 1.0 op_sel_hi:[1,0]
	v_pk_add_f32 v[48:49], v[48:49], 1.0 op_sel_hi:[1,0]
	v_pk_add_f32 v[50:51], v[50:51], 1.0 op_sel_hi:[1,0]
	v_pk_add_f32 v[52:53], v[52:53], 1.0 op_sel_hi:[1,0]
	v_pk_add_f32 v[54:55], v[54:55], 1.0 op_sel_hi:[1,0]
	v_pk_add_f32 v[56:57], v[56:57], 1.0 op_sel_hi:[1,0]
	v_pk_add_f32 v[58:59], v[58:59], 1.0 op_sel_hi:[1,0]
	v_pk_add_f32 v[60:61], v[60:61], 1.0 op_sel_hi:[1,0]
	v_pk_add_f32 v[62:63], v[62:63], 1.0 op_sel_hi:[1,0]
	v_rcp_f32_e32 v32, v32
	v_rcp_f32_e32 v33, v33
	v_rcp_f32_e32 v34, v34
	v_rcp_f32_e32 v35, v35
	v_rcp_f32_e32 v36, v36
	v_rcp_f32_e32 v37, v37
	v_rcp_f32_e32 v38, v38
	v_rcp_f32_e32 v39, v39
	v_rcp_f32_e32 v40, v40
	v_rcp_f32_e32 v41, v41
	v_rcp_f32_e32 v42, v42
	v_rcp_f32_e32 v43, v43
	v_rcp_f32_e32 v44, v44
	v_rcp_f32_e32 v45, v45
	v_rcp_f32_e32 v46, v46
	v_rcp_f32_e32 v47, v47
	v_rcp_f32_e32 v48, v48
	v_rcp_f32_e32 v49, v49
	v_rcp_f32_e32 v50, v50
	v_rcp_f32_e32 v51, v51
	v_rcp_f32_e32 v52, v52
	v_rcp_f32_e32 v53, v53
	v_rcp_f32_e32 v54, v54
	v_rcp_f32_e32 v55, v55
	v_rcp_f32_e32 v56, v56
	v_rcp_f32_e32 v57, v57
	v_rcp_f32_e32 v58, v58
	v_rcp_f32_e32 v59, v59
	v_rcp_f32_e32 v60, v60
	v_rcp_f32_e32 v61, v61
	v_rcp_f32_e32 v62, v62
	v_rcp_f32_e32 v63, v63
	s_nop 0
	v_cvt_pk_bf16_f32 v32, v32, v33
	v_cvt_pk_bf16_f32 v33, v34, v35
	v_cvt_pk_bf16_f32 v34, v36, v37
	v_cvt_pk_bf16_f32 v35, v38, v39
	v_cvt_pk_bf16_f32 v36, v40, v41
	v_cvt_pk_bf16_f32 v37, v42, v43
	v_cvt_pk_bf16_f32 v38, v44, v45
	v_cvt_pk_bf16_f32 v39, v46, v47
	v_cvt_pk_bf16_f32 v48, v48, v49
	v_cvt_pk_bf16_f32 v49, v50, v51
	v_cvt_pk_bf16_f32 v50, v52, v53
	v_cvt_pk_bf16_f32 v51, v54, v55
	v_cvt_pk_bf16_f32 v52, v56, v57
	v_cvt_pk_bf16_f32 v53, v58, v59
	v_cvt_pk_bf16_f32 v54, v60, v61
	v_cvt_pk_bf16_f32 v55, v62, v63
	v_permlane32_swap_b32_e32 v32, v34
	v_permlane32_swap_b32_e32 v33, v35
	v_permlane32_swap_b32_e32 v36, v38
	v_permlane32_swap_b32_e32 v37, v39
	v_permlane32_swap_b32_e32 v48, v50
	v_permlane32_swap_b32_e32 v49, v51
	v_permlane32_swap_b32_e32 v52, v54
	v_permlane32_swap_b32_e32 v53, v55
	s_nop 1
	s_mov_b32 vcc_lo, 0x55555555
	s_mov_b32 vcc_hi, 0x55555555
	v_cndmask_b32_dpp v128, v36, v32, vcc quad_perm:[1,0,3,2] row_mask:0xf bank_mask:0xf
	v_cndmask_b32_dpp v129, v37, v33, vcc quad_perm:[1,0,3,2] row_mask:0xf bank_mask:0xf
	v_cndmask_b32_dpp v130, v38, v34, vcc quad_perm:[1,0,3,2] row_mask:0xf bank_mask:0xf
	v_cndmask_b32_dpp v131, v39, v35, vcc quad_perm:[1,0,3,2] row_mask:0xf bank_mask:0xf
	v_cndmask_b32_dpp v136, v52, v48, vcc quad_perm:[1,0,3,2] row_mask:0xf bank_mask:0xf
	v_cndmask_b32_dpp v137, v53, v49, vcc quad_perm:[1,0,3,2] row_mask:0xf bank_mask:0xf
	v_cndmask_b32_dpp v138, v54, v50, vcc quad_perm:[1,0,3,2] row_mask:0xf bank_mask:0xf
	v_cndmask_b32_dpp v139, v55, v51, vcc quad_perm:[1,0,3,2] row_mask:0xf bank_mask:0xf
	s_mov_b32 vcc_lo, 0xaaaaaaaa
	s_mov_b32 vcc_hi, 0xaaaaaaaa
	v_cndmask_b32_dpp v132, v32, v36, vcc quad_perm:[1,0,3,2] row_mask:0xf bank_mask:0xf
	v_cndmask_b32_dpp v133, v33, v37, vcc quad_perm:[1,0,3,2] row_mask:0xf bank_mask:0xf
	v_cndmask_b32_dpp v134, v34, v38, vcc quad_perm:[1,0,3,2] row_mask:0xf bank_mask:0xf
	v_cndmask_b32_dpp v135, v35, v39, vcc quad_perm:[1,0,3,2] row_mask:0xf bank_mask:0xf
	v_cndmask_b32_dpp v140, v48, v52, vcc quad_perm:[1,0,3,2] row_mask:0xf bank_mask:0xf
	v_cndmask_b32_dpp v141, v49, v53, vcc quad_perm:[1,0,3,2] row_mask:0xf bank_mask:0xf
	v_cndmask_b32_dpp v142, v50, v54, vcc quad_perm:[1,0,3,2] row_mask:0xf bank_mask:0xf
	v_cndmask_b32_dpp v143, v51, v55, vcc quad_perm:[1,0,3,2] row_mask:0xf bank_mask:0xf
	s_nop 1
	s_mov_b32 vcc_lo, 0x33333333
	s_mov_b32 vcc_hi, 0x33333333
	v_cndmask_b32_dpp v32, v136, v128, vcc quad_perm:[2,3,0,1] row_mask:0xf bank_mask:0xf
	v_cndmask_b32_dpp v33, v137, v129, vcc quad_perm:[2,3,0,1] row_mask:0xf bank_mask:0xf
	v_cndmask_b32_dpp v34, v138, v130, vcc quad_perm:[2,3,0,1] row_mask:0xf bank_mask:0xf
	v_cndmask_b32_dpp v35, v139, v131, vcc quad_perm:[2,3,0,1] row_mask:0xf bank_mask:0xf
	v_cndmask_b32_dpp v36, v140, v132, vcc quad_perm:[2,3,0,1] row_mask:0xf bank_mask:0xf
	v_cndmask_b32_dpp v37, v141, v133, vcc quad_perm:[2,3,0,1] row_mask:0xf bank_mask:0xf
	v_cndmask_b32_dpp v38, v142, v134, vcc quad_perm:[2,3,0,1] row_mask:0xf bank_mask:0xf
	v_cndmask_b32_dpp v39, v143, v135, vcc quad_perm:[2,3,0,1] row_mask:0xf bank_mask:0xf
	s_mov_b32 vcc_lo, 0xcccccccc
	s_mov_b32 vcc_hi, 0xcccccccc
	v_cndmask_b32_dpp v48, v128, v136, vcc quad_perm:[2,3,0,1] row_mask:0xf bank_mask:0xf
	v_cndmask_b32_dpp v49, v129, v137, vcc quad_perm:[2,3,0,1] row_mask:0xf bank_mask:0xf
	v_cndmask_b32_dpp v50, v130, v138, vcc quad_perm:[2,3,0,1] row_mask:0xf bank_mask:0xf
	v_cndmask_b32_dpp v51, v131, v139, vcc quad_perm:[2,3,0,1] row_mask:0xf bank_mask:0xf
	v_cndmask_b32_dpp v52, v132, v140, vcc quad_perm:[2,3,0,1] row_mask:0xf bank_mask:0xf
	v_cndmask_b32_dpp v53, v133, v141, vcc quad_perm:[2,3,0,1] row_mask:0xf bank_mask:0xf
	v_cndmask_b32_dpp v54, v134, v142, vcc quad_perm:[2,3,0,1] row_mask:0xf bank_mask:0xf
	v_cndmask_b32_dpp v55, v135, v143, vcc quad_perm:[2,3,0,1] row_mask:0xf bank_mask:0xf
	s_add_u32 s76, s74, 0x0
	s_addc_u32 s77, s75, 0
	global_store_dwordx4 v181, v[32:35], s[76:77]
	s_add_u32 s76, s74, 0x2200
	s_addc_u32 s77, s75, 0
	global_store_dwordx4 v181, v[36:39], s[76:77]
	s_add_u32 s76, s74, 0x4400
	s_addc_u32 s77, s75, 0
	global_store_dwordx4 v181, v[48:51], s[76:77]
	s_add_u32 s76, s74, 0x6600
	s_addc_u32 s77, s75, 0
	global_store_dwordx4 v181, v[52:55], s[76:77]
	s_add_u32 s74, s74, 0x44000
	s_addc_u32 s75, s75, 0
	v_pk_fma_f32 v[64:65], v[64:65], v[174:175], v[198:199] op_sel_hi:[1,0,1]
	v_pk_fma_f32 v[66:67], v[66:67], v[174:175], v[200:201] op_sel_hi:[1,0,1]
	v_pk_fma_f32 v[68:69], v[68:69], v[174:175], v[202:203] op_sel_hi:[1,0,1]
	v_pk_fma_f32 v[70:71], v[70:71], v[174:175], v[204:205] op_sel_hi:[1,0,1]
	v_pk_fma_f32 v[72:73], v[72:73], v[174:175], v[206:207] op_sel_hi:[1,0,1]
	v_pk_fma_f32 v[74:75], v[74:75], v[174:175], v[208:209] op_sel_hi:[1,0,1]
	v_pk_fma_f32 v[76:77], v[76:77], v[174:175], v[210:211] op_sel_hi:[1,0,1]
	v_pk_fma_f32 v[78:79], v[78:79], v[174:175], v[212:213] op_sel_hi:[1,0,1]
	v_pk_fma_f32 v[80:81], v[80:81], v[174:175], v[214:215] op_sel_hi:[1,0,1]
	v_pk_fma_f32 v[82:83], v[82:83], v[174:175], v[216:217] op_sel_hi:[1,0,1]
	v_pk_fma_f32 v[84:85], v[84:85], v[174:175], v[218:219] op_sel_hi:[1,0,1]
	v_pk_fma_f32 v[86:87], v[86:87], v[174:175], v[220:221] op_sel_hi:[1,0,1]
	v_pk_fma_f32 v[88:89], v[88:89], v[174:175], v[222:223] op_sel_hi:[1,0,1]
	v_pk_fma_f32 v[90:91], v[90:91], v[174:175], v[224:225] op_sel_hi:[1,0,1]
	v_pk_fma_f32 v[92:93], v[92:93], v[174:175], v[226:227] op_sel_hi:[1,0,1]
	v_pk_fma_f32 v[94:95], v[94:95], v[174:175], v[228:229] op_sel_hi:[1,0,1]
	v_exp_f32_e32 v64, v64
	v_exp_f32_e32 v65, v65
	v_exp_f32_e32 v66, v66
	v_exp_f32_e32 v67, v67
	v_exp_f32_e32 v68, v68
	v_exp_f32_e32 v69, v69
	v_exp_f32_e32 v70, v70
	v_exp_f32_e32 v71, v71
	v_exp_f32_e32 v72, v72
	v_exp_f32_e32 v73, v73
	v_exp_f32_e32 v74, v74
	v_exp_f32_e32 v75, v75
	v_exp_f32_e32 v76, v76
	v_exp_f32_e32 v77, v77
	v_exp_f32_e32 v78, v78
	v_exp_f32_e32 v79, v79
	v_exp_f32_e32 v80, v80
	v_exp_f32_e32 v81, v81
	v_exp_f32_e32 v82, v82
	v_exp_f32_e32 v83, v83
	v_exp_f32_e32 v84, v84
	v_exp_f32_e32 v85, v85
	v_exp_f32_e32 v86, v86
	v_exp_f32_e32 v87, v87
	v_exp_f32_e32 v88, v88
	v_exp_f32_e32 v89, v89
	v_exp_f32_e32 v90, v90
	v_exp_f32_e32 v91, v91
	v_exp_f32_e32 v92, v92
	v_exp_f32_e32 v93, v93
	v_exp_f32_e32 v94, v94
	v_exp_f32_e32 v95, v95
	v_pk_add_f32 v[64:65], v[64:65], 1.0 op_sel_hi:[1,0]
	v_pk_add_f32 v[66:67], v[66:67], 1.0 op_sel_hi:[1,0]
	v_pk_add_f32 v[68:69], v[68:69], 1.0 op_sel_hi:[1,0]
	v_pk_add_f32 v[70:71], v[70:71], 1.0 op_sel_hi:[1,0]
	v_pk_add_f32 v[72:73], v[72:73], 1.0 op_sel_hi:[1,0]
	v_pk_add_f32 v[74:75], v[74:75], 1.0 op_sel_hi:[1,0]
	v_pk_add_f32 v[76:77], v[76:77], 1.0 op_sel_hi:[1,0]
	v_pk_add_f32 v[78:79], v[78:79], 1.0 op_sel_hi:[1,0]
	v_pk_add_f32 v[80:81], v[80:81], 1.0 op_sel_hi:[1,0]
	v_pk_add_f32 v[82:83], v[82:83], 1.0 op_sel_hi:[1,0]
	v_pk_add_f32 v[84:85], v[84:85], 1.0 op_sel_hi:[1,0]
	v_pk_add_f32 v[86:87], v[86:87], 1.0 op_sel_hi:[1,0]
	v_pk_add_f32 v[88:89], v[88:89], 1.0 op_sel_hi:[1,0]
	v_pk_add_f32 v[90:91], v[90:91], 1.0 op_sel_hi:[1,0]
	v_pk_add_f32 v[92:93], v[92:93], 1.0 op_sel_hi:[1,0]
	v_pk_add_f32 v[94:95], v[94:95], 1.0 op_sel_hi:[1,0]
	v_rcp_f32_e32 v64, v64
	v_rcp_f32_e32 v65, v65
	v_rcp_f32_e32 v66, v66
	v_rcp_f32_e32 v67, v67
	v_rcp_f32_e32 v68, v68
	v_rcp_f32_e32 v69, v69
	v_rcp_f32_e32 v70, v70
	v_rcp_f32_e32 v71, v71
	v_rcp_f32_e32 v72, v72
	v_rcp_f32_e32 v73, v73
	v_rcp_f32_e32 v74, v74
	v_rcp_f32_e32 v75, v75
	v_rcp_f32_e32 v76, v76
	v_rcp_f32_e32 v77, v77
	v_rcp_f32_e32 v78, v78
	v_rcp_f32_e32 v79, v79
	v_rcp_f32_e32 v80, v80
	v_rcp_f32_e32 v81, v81
	v_rcp_f32_e32 v82, v82
	v_rcp_f32_e32 v83, v83
	v_rcp_f32_e32 v84, v84
	v_rcp_f32_e32 v85, v85
	v_rcp_f32_e32 v86, v86
	v_rcp_f32_e32 v87, v87
	v_rcp_f32_e32 v88, v88
	v_rcp_f32_e32 v89, v89
	v_rcp_f32_e32 v90, v90
	v_rcp_f32_e32 v91, v91
	v_rcp_f32_e32 v92, v92
	v_rcp_f32_e32 v93, v93
	v_rcp_f32_e32 v94, v94
	v_rcp_f32_e32 v95, v95
	s_nop 0
	v_cvt_pk_bf16_f32 v64, v64, v65
	v_cvt_pk_bf16_f32 v65, v66, v67
	v_cvt_pk_bf16_f32 v66, v68, v69
	v_cvt_pk_bf16_f32 v67, v70, v71
	v_cvt_pk_bf16_f32 v68, v72, v73
	v_cvt_pk_bf16_f32 v69, v74, v75
	v_cvt_pk_bf16_f32 v70, v76, v77
	v_cvt_pk_bf16_f32 v71, v78, v79
	v_cvt_pk_bf16_f32 v80, v80, v81
	v_cvt_pk_bf16_f32 v81, v82, v83
	v_cvt_pk_bf16_f32 v82, v84, v85
	v_cvt_pk_bf16_f32 v83, v86, v87
	v_cvt_pk_bf16_f32 v84, v88, v89
	v_cvt_pk_bf16_f32 v85, v90, v91
	v_cvt_pk_bf16_f32 v86, v92, v93
	v_cvt_pk_bf16_f32 v87, v94, v95
	v_permlane32_swap_b32_e32 v64, v66
	v_permlane32_swap_b32_e32 v65, v67
	v_permlane32_swap_b32_e32 v68, v70
	v_permlane32_swap_b32_e32 v69, v71
	v_permlane32_swap_b32_e32 v80, v82
	v_permlane32_swap_b32_e32 v81, v83
	v_permlane32_swap_b32_e32 v84, v86
	v_permlane32_swap_b32_e32 v85, v87
	s_nop 1
	s_mov_b32 vcc_lo, 0x55555555
	s_mov_b32 vcc_hi, 0x55555555
	v_cndmask_b32_dpp v128, v68, v64, vcc quad_perm:[1,0,3,2] row_mask:0xf bank_mask:0xf
	v_cndmask_b32_dpp v129, v69, v65, vcc quad_perm:[1,0,3,2] row_mask:0xf bank_mask:0xf
	v_cndmask_b32_dpp v130, v70, v66, vcc quad_perm:[1,0,3,2] row_mask:0xf bank_mask:0xf
	v_cndmask_b32_dpp v131, v71, v67, vcc quad_perm:[1,0,3,2] row_mask:0xf bank_mask:0xf
	v_cndmask_b32_dpp v136, v84, v80, vcc quad_perm:[1,0,3,2] row_mask:0xf bank_mask:0xf
	v_cndmask_b32_dpp v137, v85, v81, vcc quad_perm:[1,0,3,2] row_mask:0xf bank_mask:0xf
	v_cndmask_b32_dpp v138, v86, v82, vcc quad_perm:[1,0,3,2] row_mask:0xf bank_mask:0xf
	v_cndmask_b32_dpp v139, v87, v83, vcc quad_perm:[1,0,3,2] row_mask:0xf bank_mask:0xf
	s_mov_b32 vcc_lo, 0xaaaaaaaa
	s_mov_b32 vcc_hi, 0xaaaaaaaa
	v_cndmask_b32_dpp v132, v64, v68, vcc quad_perm:[1,0,3,2] row_mask:0xf bank_mask:0xf
	v_cndmask_b32_dpp v133, v65, v69, vcc quad_perm:[1,0,3,2] row_mask:0xf bank_mask:0xf
	v_cndmask_b32_dpp v134, v66, v70, vcc quad_perm:[1,0,3,2] row_mask:0xf bank_mask:0xf
	v_cndmask_b32_dpp v135, v67, v71, vcc quad_perm:[1,0,3,2] row_mask:0xf bank_mask:0xf
	v_cndmask_b32_dpp v140, v80, v84, vcc quad_perm:[1,0,3,2] row_mask:0xf bank_mask:0xf
	v_cndmask_b32_dpp v141, v81, v85, vcc quad_perm:[1,0,3,2] row_mask:0xf bank_mask:0xf
	v_cndmask_b32_dpp v142, v82, v86, vcc quad_perm:[1,0,3,2] row_mask:0xf bank_mask:0xf
	v_cndmask_b32_dpp v143, v83, v87, vcc quad_perm:[1,0,3,2] row_mask:0xf bank_mask:0xf
	s_nop 1
	s_mov_b32 vcc_lo, 0x33333333
	s_mov_b32 vcc_hi, 0x33333333
	v_cndmask_b32_dpp v64, v136, v128, vcc quad_perm:[2,3,0,1] row_mask:0xf bank_mask:0xf
	v_cndmask_b32_dpp v65, v137, v129, vcc quad_perm:[2,3,0,1] row_mask:0xf bank_mask:0xf
	v_cndmask_b32_dpp v66, v138, v130, vcc quad_perm:[2,3,0,1] row_mask:0xf bank_mask:0xf
	v_cndmask_b32_dpp v67, v139, v131, vcc quad_perm:[2,3,0,1] row_mask:0xf bank_mask:0xf
	v_cndmask_b32_dpp v68, v140, v132, vcc quad_perm:[2,3,0,1] row_mask:0xf bank_mask:0xf
	v_cndmask_b32_dpp v69, v141, v133, vcc quad_perm:[2,3,0,1] row_mask:0xf bank_mask:0xf
	v_cndmask_b32_dpp v70, v142, v134, vcc quad_perm:[2,3,0,1] row_mask:0xf bank_mask:0xf
	v_cndmask_b32_dpp v71, v143, v135, vcc quad_perm:[2,3,0,1] row_mask:0xf bank_mask:0xf
	s_mov_b32 vcc_lo, 0xcccccccc
	s_mov_b32 vcc_hi, 0xcccccccc
	v_cndmask_b32_dpp v80, v128, v136, vcc quad_perm:[2,3,0,1] row_mask:0xf bank_mask:0xf
	v_cndmask_b32_dpp v81, v129, v137, vcc quad_perm:[2,3,0,1] row_mask:0xf bank_mask:0xf
	v_cndmask_b32_dpp v82, v130, v138, vcc quad_perm:[2,3,0,1] row_mask:0xf bank_mask:0xf
	v_cndmask_b32_dpp v83, v131, v139, vcc quad_perm:[2,3,0,1] row_mask:0xf bank_mask:0xf
	v_cndmask_b32_dpp v84, v132, v140, vcc quad_perm:[2,3,0,1] row_mask:0xf bank_mask:0xf
	v_cndmask_b32_dpp v85, v133, v141, vcc quad_perm:[2,3,0,1] row_mask:0xf bank_mask:0xf
	v_cndmask_b32_dpp v86, v134, v142, vcc quad_perm:[2,3,0,1] row_mask:0xf bank_mask:0xf
	v_cndmask_b32_dpp v87, v135, v143, vcc quad_perm:[2,3,0,1] row_mask:0xf bank_mask:0xf
	s_add_u32 s76, s74, 0x0
	s_addc_u32 s77, s75, 0
	global_store_dwordx4 v181, v[64:67], s[76:77]
	s_add_u32 s76, s74, 0x2200
	s_addc_u32 s77, s75, 0
	global_store_dwordx4 v181, v[68:71], s[76:77]
	s_add_u32 s76, s74, 0x4400
	s_addc_u32 s77, s75, 0
	global_store_dwordx4 v181, v[80:83], s[76:77]
	s_add_u32 s76, s74, 0x6600
	s_addc_u32 s77, s75, 0
	global_store_dwordx4 v181, v[84:87], s[76:77]
	s_add_u32 s74, s74, 0x44000
	s_addc_u32 s75, s75, 0
	v_pk_fma_f32 v[96:97], v[96:97], v[174:175], v[198:199] op_sel:[0,1,0] op_sel_hi:[1,1,1]
	v_pk_fma_f32 v[98:99], v[98:99], v[174:175], v[200:201] op_sel:[0,1,0] op_sel_hi:[1,1,1]
	v_pk_fma_f32 v[100:101], v[100:101], v[174:175], v[202:203] op_sel:[0,1,0] op_sel_hi:[1,1,1]
	v_pk_fma_f32 v[102:103], v[102:103], v[174:175], v[204:205] op_sel:[0,1,0] op_sel_hi:[1,1,1]
	v_pk_fma_f32 v[104:105], v[104:105], v[174:175], v[206:207] op_sel:[0,1,0] op_sel_hi:[1,1,1]
	v_pk_fma_f32 v[106:107], v[106:107], v[174:175], v[208:209] op_sel:[0,1,0] op_sel_hi:[1,1,1]
	v_pk_fma_f32 v[108:109], v[108:109], v[174:175], v[210:211] op_sel:[0,1,0] op_sel_hi:[1,1,1]
	v_pk_fma_f32 v[110:111], v[110:111], v[174:175], v[212:213] op_sel:[0,1,0] op_sel_hi:[1,1,1]
	v_pk_fma_f32 v[112:113], v[112:113], v[174:175], v[214:215] op_sel:[0,1,0] op_sel_hi:[1,1,1]
	v_pk_fma_f32 v[114:115], v[114:115], v[174:175], v[216:217] op_sel:[0,1,0] op_sel_hi:[1,1,1]
	v_pk_fma_f32 v[116:117], v[116:117], v[174:175], v[218:219] op_sel:[0,1,0] op_sel_hi:[1,1,1]
	v_pk_fma_f32 v[118:119], v[118:119], v[174:175], v[220:221] op_sel:[0,1,0] op_sel_hi:[1,1,1]
	v_pk_fma_f32 v[120:121], v[120:121], v[174:175], v[222:223] op_sel:[0,1,0] op_sel_hi:[1,1,1]
	v_pk_fma_f32 v[122:123], v[122:123], v[174:175], v[224:225] op_sel:[0,1,0] op_sel_hi:[1,1,1]
	v_pk_fma_f32 v[124:125], v[124:125], v[174:175], v[226:227] op_sel:[0,1,0] op_sel_hi:[1,1,1]
	v_pk_fma_f32 v[126:127], v[126:127], v[174:175], v[228:229] op_sel:[0,1,0] op_sel_hi:[1,1,1]
	v_exp_f32_e32 v96, v96
	v_exp_f32_e32 v97, v97
	v_exp_f32_e32 v98, v98
	v_exp_f32_e32 v99, v99
	v_exp_f32_e32 v100, v100
	v_exp_f32_e32 v101, v101
	v_exp_f32_e32 v102, v102
	v_exp_f32_e32 v103, v103
	v_exp_f32_e32 v104, v104
	v_exp_f32_e32 v105, v105
	v_exp_f32_e32 v106, v106
	v_exp_f32_e32 v107, v107
	v_exp_f32_e32 v108, v108
	v_exp_f32_e32 v109, v109
	v_exp_f32_e32 v110, v110
	v_exp_f32_e32 v111, v111
	v_exp_f32_e32 v112, v112
	v_exp_f32_e32 v113, v113
	v_exp_f32_e32 v114, v114
	v_exp_f32_e32 v115, v115
	v_exp_f32_e32 v116, v116
	v_exp_f32_e32 v117, v117
	v_exp_f32_e32 v118, v118
	v_exp_f32_e32 v119, v119
	v_exp_f32_e32 v120, v120
	v_exp_f32_e32 v121, v121
	v_exp_f32_e32 v122, v122
	v_exp_f32_e32 v123, v123
	v_exp_f32_e32 v124, v124
	v_exp_f32_e32 v125, v125
	v_exp_f32_e32 v126, v126
	v_exp_f32_e32 v127, v127
	v_pk_add_f32 v[96:97], v[96:97], 1.0 op_sel_hi:[1,0]
	v_pk_add_f32 v[98:99], v[98:99], 1.0 op_sel_hi:[1,0]
	v_pk_add_f32 v[100:101], v[100:101], 1.0 op_sel_hi:[1,0]
	v_pk_add_f32 v[102:103], v[102:103], 1.0 op_sel_hi:[1,0]
	v_pk_add_f32 v[104:105], v[104:105], 1.0 op_sel_hi:[1,0]
	v_pk_add_f32 v[106:107], v[106:107], 1.0 op_sel_hi:[1,0]
	v_pk_add_f32 v[108:109], v[108:109], 1.0 op_sel_hi:[1,0]
	v_pk_add_f32 v[110:111], v[110:111], 1.0 op_sel_hi:[1,0]
	v_pk_add_f32 v[112:113], v[112:113], 1.0 op_sel_hi:[1,0]
	v_pk_add_f32 v[114:115], v[114:115], 1.0 op_sel_hi:[1,0]
	v_pk_add_f32 v[116:117], v[116:117], 1.0 op_sel_hi:[1,0]
	v_pk_add_f32 v[118:119], v[118:119], 1.0 op_sel_hi:[1,0]
	v_pk_add_f32 v[120:121], v[120:121], 1.0 op_sel_hi:[1,0]
	v_pk_add_f32 v[122:123], v[122:123], 1.0 op_sel_hi:[1,0]
	v_pk_add_f32 v[124:125], v[124:125], 1.0 op_sel_hi:[1,0]
	v_pk_add_f32 v[126:127], v[126:127], 1.0 op_sel_hi:[1,0]
	v_rcp_f32_e32 v96, v96
	v_rcp_f32_e32 v97, v97
	v_rcp_f32_e32 v98, v98
	v_rcp_f32_e32 v99, v99
	v_rcp_f32_e32 v100, v100
	v_rcp_f32_e32 v101, v101
	v_rcp_f32_e32 v102, v102
	v_rcp_f32_e32 v103, v103
	v_rcp_f32_e32 v104, v104
	v_rcp_f32_e32 v105, v105
	v_rcp_f32_e32 v106, v106
	v_rcp_f32_e32 v107, v107
	v_rcp_f32_e32 v108, v108
	v_rcp_f32_e32 v109, v109
	v_rcp_f32_e32 v110, v110
	v_rcp_f32_e32 v111, v111
	v_rcp_f32_e32 v112, v112
	v_rcp_f32_e32 v113, v113
	v_rcp_f32_e32 v114, v114
	v_rcp_f32_e32 v115, v115
	v_rcp_f32_e32 v116, v116
	v_rcp_f32_e32 v117, v117
	v_rcp_f32_e32 v118, v118
	v_rcp_f32_e32 v119, v119
	v_rcp_f32_e32 v120, v120
	v_rcp_f32_e32 v121, v121
	v_rcp_f32_e32 v122, v122
	v_rcp_f32_e32 v123, v123
	v_rcp_f32_e32 v124, v124
	v_rcp_f32_e32 v125, v125
	v_rcp_f32_e32 v126, v126
	v_rcp_f32_e32 v127, v127
	s_nop 0
	v_cvt_pk_bf16_f32 v96, v96, v97
	v_cvt_pk_bf16_f32 v97, v98, v99
	v_cvt_pk_bf16_f32 v98, v100, v101
	v_cvt_pk_bf16_f32 v99, v102, v103
	v_cvt_pk_bf16_f32 v100, v104, v105
	v_cvt_pk_bf16_f32 v101, v106, v107
	v_cvt_pk_bf16_f32 v102, v108, v109
	v_cvt_pk_bf16_f32 v103, v110, v111
	v_cvt_pk_bf16_f32 v112, v112, v113
	v_cvt_pk_bf16_f32 v113, v114, v115
	v_cvt_pk_bf16_f32 v114, v116, v117
	v_cvt_pk_bf16_f32 v115, v118, v119
	v_cvt_pk_bf16_f32 v116, v120, v121
	v_cvt_pk_bf16_f32 v117, v122, v123
	v_cvt_pk_bf16_f32 v118, v124, v125
	v_cvt_pk_bf16_f32 v119, v126, v127
	v_permlane32_swap_b32_e32 v96, v98
	v_permlane32_swap_b32_e32 v97, v99
	v_permlane32_swap_b32_e32 v100, v102
	v_permlane32_swap_b32_e32 v101, v103
	v_permlane32_swap_b32_e32 v112, v114
	v_permlane32_swap_b32_e32 v113, v115
	v_permlane32_swap_b32_e32 v116, v118
	v_permlane32_swap_b32_e32 v117, v119
	s_nop 1
	s_mov_b32 vcc_lo, 0x55555555
	s_mov_b32 vcc_hi, 0x55555555
	v_cndmask_b32_dpp v128, v100, v96, vcc quad_perm:[1,0,3,2] row_mask:0xf bank_mask:0xf
	v_cndmask_b32_dpp v129, v101, v97, vcc quad_perm:[1,0,3,2] row_mask:0xf bank_mask:0xf
	v_cndmask_b32_dpp v130, v102, v98, vcc quad_perm:[1,0,3,2] row_mask:0xf bank_mask:0xf
	v_cndmask_b32_dpp v131, v103, v99, vcc quad_perm:[1,0,3,2] row_mask:0xf bank_mask:0xf
	v_cndmask_b32_dpp v136, v116, v112, vcc quad_perm:[1,0,3,2] row_mask:0xf bank_mask:0xf
	v_cndmask_b32_dpp v137, v117, v113, vcc quad_perm:[1,0,3,2] row_mask:0xf bank_mask:0xf
	v_cndmask_b32_dpp v138, v118, v114, vcc quad_perm:[1,0,3,2] row_mask:0xf bank_mask:0xf
	v_cndmask_b32_dpp v139, v119, v115, vcc quad_perm:[1,0,3,2] row_mask:0xf bank_mask:0xf
	s_mov_b32 vcc_lo, 0xaaaaaaaa
	s_mov_b32 vcc_hi, 0xaaaaaaaa
	v_cndmask_b32_dpp v132, v96, v100, vcc quad_perm:[1,0,3,2] row_mask:0xf bank_mask:0xf
	v_cndmask_b32_dpp v133, v97, v101, vcc quad_perm:[1,0,3,2] row_mask:0xf bank_mask:0xf
	v_cndmask_b32_dpp v134, v98, v102, vcc quad_perm:[1,0,3,2] row_mask:0xf bank_mask:0xf
	v_cndmask_b32_dpp v135, v99, v103, vcc quad_perm:[1,0,3,2] row_mask:0xf bank_mask:0xf
	v_cndmask_b32_dpp v140, v112, v116, vcc quad_perm:[1,0,3,2] row_mask:0xf bank_mask:0xf
	v_cndmask_b32_dpp v141, v113, v117, vcc quad_perm:[1,0,3,2] row_mask:0xf bank_mask:0xf
	v_cndmask_b32_dpp v142, v114, v118, vcc quad_perm:[1,0,3,2] row_mask:0xf bank_mask:0xf
	v_cndmask_b32_dpp v143, v115, v119, vcc quad_perm:[1,0,3,2] row_mask:0xf bank_mask:0xf
	s_nop 1
	s_mov_b32 vcc_lo, 0x33333333
	s_mov_b32 vcc_hi, 0x33333333
	v_cndmask_b32_dpp v96, v136, v128, vcc quad_perm:[2,3,0,1] row_mask:0xf bank_mask:0xf
	v_cndmask_b32_dpp v97, v137, v129, vcc quad_perm:[2,3,0,1] row_mask:0xf bank_mask:0xf
	v_cndmask_b32_dpp v98, v138, v130, vcc quad_perm:[2,3,0,1] row_mask:0xf bank_mask:0xf
	v_cndmask_b32_dpp v99, v139, v131, vcc quad_perm:[2,3,0,1] row_mask:0xf bank_mask:0xf
	v_cndmask_b32_dpp v100, v140, v132, vcc quad_perm:[2,3,0,1] row_mask:0xf bank_mask:0xf
	v_cndmask_b32_dpp v101, v141, v133, vcc quad_perm:[2,3,0,1] row_mask:0xf bank_mask:0xf
	v_cndmask_b32_dpp v102, v142, v134, vcc quad_perm:[2,3,0,1] row_mask:0xf bank_mask:0xf
	v_cndmask_b32_dpp v103, v143, v135, vcc quad_perm:[2,3,0,1] row_mask:0xf bank_mask:0xf
	s_mov_b32 vcc_lo, 0xcccccccc
	s_mov_b32 vcc_hi, 0xcccccccc
	v_cndmask_b32_dpp v112, v128, v136, vcc quad_perm:[2,3,0,1] row_mask:0xf bank_mask:0xf
	v_cndmask_b32_dpp v113, v129, v137, vcc quad_perm:[2,3,0,1] row_mask:0xf bank_mask:0xf
	v_cndmask_b32_dpp v114, v130, v138, vcc quad_perm:[2,3,0,1] row_mask:0xf bank_mask:0xf
	v_cndmask_b32_dpp v115, v131, v139, vcc quad_perm:[2,3,0,1] row_mask:0xf bank_mask:0xf
	v_cndmask_b32_dpp v116, v132, v140, vcc quad_perm:[2,3,0,1] row_mask:0xf bank_mask:0xf
	v_cndmask_b32_dpp v117, v133, v141, vcc quad_perm:[2,3,0,1] row_mask:0xf bank_mask:0xf
	v_cndmask_b32_dpp v118, v134, v142, vcc quad_perm:[2,3,0,1] row_mask:0xf bank_mask:0xf
	v_cndmask_b32_dpp v119, v135, v143, vcc quad_perm:[2,3,0,1] row_mask:0xf bank_mask:0xf
	s_add_u32 s76, s74, 0x0
	s_addc_u32 s77, s75, 0
	global_store_dwordx4 v181, v[96:99], s[76:77]
	s_add_u32 s76, s74, 0x2200
	s_addc_u32 s77, s75, 0
	global_store_dwordx4 v181, v[100:103], s[76:77]
	s_add_u32 s76, s74, 0x4400
	s_addc_u32 s77, s75, 0
	global_store_dwordx4 v181, v[112:115], s[76:77]
	s_add_u32 s76, s74, 0x6600
	s_addc_u32 s77, s75, 0
	global_store_dwordx4 v181, v[116:119], s[76:77]
	s_branch .Lpe_ret_L1
